# nt also on the other read-once input streams: p being converted, the input x and layer-0 f32 weights in the prologue
# speedup vs baseline: 1.0216x; 1.0066x over previous
; __device__ __forceinline__ void wconv_item(const float* W, int K, int Norig, int Nphys, bf16_t* WT, const float* gA, const float* gB, int split, int mapid, LAS float* scr, int item, int lane) {
;     const int nblk = Nphys / 32, kb = item / nblk, nb = item % nblk, k0 = 64 * kb, n0 = 32 * nb;
;     const int norig = colmap(mapid, n0 + (lane & 31));
;     float wv[32];
; #pragma unroll
;     for (int i = 0; i < 32; ++i) { const int k = k0 + 2 * i + (lane >> 5); wv[i] = (norig >= 0) ? W[(size_t)k * Norig + norig] : 0.f; }
; #pragma unroll
;     for (int i = 0; i < 32; ++i) { const int kk = 2 * i + (lane >> 5), k = k0 + kk;
;         float v = wv[i];
;         if (gA) v *= (k < split ? gA[k] : gB[k - split]);
;         scr[kk * 33 + (lane & 31)] = v; }
; template <class AP> __device__ __forceinline__ void convert_weights(AP a, int L, bf16_t* wb, LAS float* scr, int gw, int NGW, int lane) {
;     ...
;         if (r < I0) { wconv_item(w_in, 1024, INC, INP, wb + WO_IN, g_mix, g_mix, 1024, 0, scr, r, lane); continue; } r -= I0;
;         if (r < I1) { wconv_item(w_uq, QL, 768, 768, wb + WO_UQ, g_ql, g_ql, QL, 1, scr, r, lane); continue; } r -= I1;
;         if (r < I2) { wconv_item(w_ukv, KVL, 1024, 1024, wb + WO_UKV, g_kvl, g_kvl, KVL, 2, scr, r, lane); continue; } r -= I2;
;         if (r < I3) { wconv_item(w_o, 1024, 1024, 1024, wb + WO_O, g_oa, g_oc, 512, 3, scr, r, lane); continue; } r -= I3;
;         if (r < I4) { wconv_item(w_up, 1024, FF, FF, wb + WO_UP, g_mlp, g_mlp, 1024, 3, scr, r, lane); continue; } r -= I4;
;         if (r < I5) { wconv_item(w_dn, FF, 1024, 1024, wb + WO_DN, nullptr, nullptr, 0, 3, scr, r, lane); continue; } r -= I5;
;         if (r < I6) { wconv_item(w_g, 1024, 1024, 1024, wb + WO_G, g_ple, g_ple, 1024, 3, scr, r, lane); continue; } r -= I6;
;         wconv_item(w_ple, PLE, 1024, 1024, wb + WO_PLE, nullptr, nullptr, 0, 3, scr, r, lane);
.LBB0_12:
	s_cmpk_gt_i32 s74, 0x47f
	s_mov_b64 s[4:5], -1
	s_cbranch_scc0 .LBB0_106
	s_cmpk_gt_u32 s74, 0x50f
	s_cbranch_scc0 .LBB0_87
	s_cmpk_gt_u32 s74, 0x58f
	s_cbranch_scc0 .LBB0_68
	s_cmpk_gt_u32 s74, 0x78f
	s_cbranch_scc0 .LBB0_53
	s_cmpk_gt_u32 s74, 0xf8f
	s_cbranch_scc0 .LBB0_38
	s_cmpk_gt_u32 s74, 0x178f
	s_cbranch_scc0 .LBB0_35
	s_cmpk_gt_u32 s74, 0x198f
	s_cbranch_scc0 .LBB0_20
	s_add_i32 s4, s87, 0xfffcce00
	s_and_b32 s4, s4, 0x3e0
	s_and_b32 s5, s89, 0x1c0
	v_or_b32_e32 v4, s4, v1
	v_or_b32_e32 v24, s5, v2
	v_lshlrev_b32_e32 v4, 2, v4
	v_lshl_add_u64 v[22:23], s[6:7], 0, v[4:5]
	v_lshlrev_b32_e32 v4, 12, v24
	v_lshl_add_u64 v[22:23], v[22:23], 0, v[4:5]
	v_add_co_u32_e32 v24, vcc, 0x2000, v22
	s_lshl_b32 s34, s5, 1
	s_nop 0
	v_addc_co_u32_e32 v25, vcc, 0, v23, vcc
	v_add_co_u32_e32 v26, vcc, 0x4000, v22
	s_nop 1
	v_addc_co_u32_e32 v27, vcc, 0, v23, vcc
	v_add_co_u32_e32 v28, vcc, 0x6000, v22
	s_nop 1
	v_addc_co_u32_e32 v29, vcc, 0, v23, vcc
	v_add_co_u32_e32 v30, vcc, 0x8000, v22
	s_nop 1
	v_addc_co_u32_e32 v31, vcc, 0, v23, vcc
	v_add_co_u32_e32 v32, vcc, 0xa000, v22
	s_nop 1
	v_addc_co_u32_e32 v33, vcc, 0, v23, vcc
	v_add_co_u32_e32 v34, vcc, 0xc000, v22
	s_nop 1
	v_addc_co_u32_e32 v35, vcc, 0, v23, vcc
	v_add_co_u32_e32 v36, vcc, 0xe000, v22
	s_nop 1
	v_addc_co_u32_e32 v37, vcc, 0, v23, vcc
	global_load_dword v4, v[22:23], off nt
	global_load_dword v40, v[24:25], off nt
	global_load_dword v41, v[26:27], off nt
	global_load_dword v42, v[28:29], off nt
	global_load_dword v43, v[30:31], off nt
	global_load_dword v93, v[32:33], off nt
	global_load_dword v94, v[34:35], off nt
	global_load_dword v95, v[36:37], off nt
	v_add_co_u32_e32 v24, vcc, 0x10000, v22
	s_nop 1
	v_addc_co_u32_e32 v25, vcc, 0, v23, vcc
	v_add_co_u32_e32 v26, vcc, 0x12000, v22
	s_nop 1
	v_addc_co_u32_e32 v27, vcc, 0, v23, vcc
	v_add_co_u32_e32 v28, vcc, 0x14000, v22
	s_nop 1
	v_addc_co_u32_e32 v29, vcc, 0, v23, vcc
	v_add_co_u32_e32 v30, vcc, 0x16000, v22
	s_nop 1
	v_addc_co_u32_e32 v31, vcc, 0, v23, vcc
	v_add_co_u32_e32 v32, vcc, 0x18000, v22
	s_nop 1
	v_addc_co_u32_e32 v33, vcc, 0, v23, vcc
	v_add_co_u32_e32 v34, vcc, 0x1a000, v22
	s_nop 1
	v_addc_co_u32_e32 v35, vcc, 0, v23, vcc
	v_add_co_u32_e32 v36, vcc, 0x1c000, v22
	s_nop 1
	v_addc_co_u32_e32 v37, vcc, 0, v23, vcc
	v_add_co_u32_e32 v38, vcc, 0x1e000, v22
	s_nop 1
	v_addc_co_u32_e32 v39, vcc, 0, v23, vcc
	global_load_dword v96, v[24:25], off nt
	global_load_dword v97, v[26:27], off nt
	global_load_dword v98, v[28:29], off nt
	global_load_dword v99, v[30:31], off nt
	global_load_dword v100, v[32:33], off nt
	global_load_dword v101, v[34:35], off nt
	global_load_dword v102, v[36:37], off nt
	global_load_dword v103, v[38:39], off nt
	v_add_co_u32_e32 v24, vcc, 0x20000, v22
	s_nop 1
	v_addc_co_u32_e32 v25, vcc, 0, v23, vcc
	v_add_co_u32_e32 v26, vcc, 0x22000, v22
	s_nop 1
	v_addc_co_u32_e32 v27, vcc, 0, v23, vcc
	v_add_co_u32_e32 v28, vcc, 0x24000, v22
	s_nop 1
	v_addc_co_u32_e32 v29, vcc, 0, v23, vcc
	v_add_co_u32_e32 v30, vcc, 0x26000, v22
	s_nop 1
	v_addc_co_u32_e32 v31, vcc, 0, v23, vcc
	v_add_co_u32_e32 v32, vcc, 0x28000, v22
	s_nop 1
	v_addc_co_u32_e32 v33, vcc, 0, v23, vcc
	v_add_co_u32_e32 v34, vcc, 0x2a000, v22
	s_nop 1
	v_addc_co_u32_e32 v35, vcc, 0, v23, vcc
	v_add_co_u32_e32 v36, vcc, 0x2c000, v22
	s_nop 1
	v_addc_co_u32_e32 v37, vcc, 0, v23, vcc
	v_add_co_u32_e32 v38, vcc, 0x2e000, v22
	s_nop 1
	v_addc_co_u32_e32 v39, vcc, 0, v23, vcc
	global_load_dword v104, v[24:25], off nt
	global_load_dword v105, v[26:27], off nt
	global_load_dword v106, v[28:29], off nt
	global_load_dword v107, v[30:31], off nt
	global_load_dword v108, v[32:33], off nt
	global_load_dword v109, v[34:35], off nt
	global_load_dword v110, v[36:37], off nt
	s_nop 0
	global_load_dword v38, v[38:39], off nt
	v_add_co_u32_e32 v24, vcc, 0x30000, v22
	s_nop 1
	v_addc_co_u32_e32 v25, vcc, 0, v23, vcc
	v_add_co_u32_e32 v26, vcc, 0x32000, v22
	s_nop 1
	v_addc_co_u32_e32 v27, vcc, 0, v23, vcc
	v_add_co_u32_e32 v28, vcc, 0x34000, v22
	s_nop 1
	v_addc_co_u32_e32 v29, vcc, 0, v23, vcc
	v_add_co_u32_e32 v30, vcc, 0x36000, v22
	s_nop 1
	v_addc_co_u32_e32 v31, vcc, 0, v23, vcc
	v_add_co_u32_e32 v32, vcc, 0x38000, v22
	s_nop 1
	v_addc_co_u32_e32 v33, vcc, 0, v23, vcc
	v_add_co_u32_e32 v34, vcc, 0x3a000, v22
	s_nop 1
	v_addc_co_u32_e32 v35, vcc, 0, v23, vcc
	v_add_co_u32_e32 v36, vcc, 0x3c000, v22
	s_nop 1
	v_addc_co_u32_e32 v37, vcc, 0, v23, vcc
	v_add_co_u32_e32 v22, vcc, 0x3e000, v22
	s_nop 1
	v_addc_co_u32_e32 v23, vcc, 0, v23, vcc
	global_load_dword v24, v[24:25], off nt
	s_nop 0
	global_load_dword v25, v[26:27], off nt
	s_nop 0
	global_load_dword v26, v[28:29], off nt
	global_load_dword v27, v[30:31], off nt
	s_nop 0
	global_load_dword v28, v[32:33], off nt
	global_load_dword v29, v[34:35], off nt
	global_load_dword v30, v[36:37], off nt
	s_nop 0
	global_load_dword v22, v[22:23], off nt
	s_waitcnt vmcnt(30)
	ds_write2_b32 v45, v4, v40 offset1:66
	s_waitcnt vmcnt(28)
	ds_write2_b32 v45, v41, v42 offset0:132 offset1:198
	v_add_u32_e32 v4, 0x400, v45
	s_waitcnt vmcnt(26)
	ds_write2_b32 v4, v43, v93 offset0:8 offset1:74
	s_waitcnt vmcnt(24)
	ds_write2_b32 v4, v94, v95 offset0:140 offset1:206
	v_add_u32_e32 v4, 0x800, v45
	s_waitcnt vmcnt(22)
	ds_write2_b32 v4, v96, v97 offset0:16 offset1:82
	s_waitcnt vmcnt(20)
	ds_write2_b32 v4, v98, v99 offset0:148 offset1:214
	v_add_u32_e32 v4, 0xc00, v45
	s_waitcnt vmcnt(18)
	ds_write2_b32 v4, v100, v101 offset0:24 offset1:90
	s_waitcnt vmcnt(16)
	ds_write2_b32 v4, v102, v103 offset0:156 offset1:222
	v_add_u32_e32 v4, 0x1000, v45
	s_waitcnt vmcnt(14)
	ds_write2_b32 v4, v104, v105 offset0:32 offset1:98
	s_waitcnt vmcnt(12)
; #define LAS __attribute__((address_space(3)))
; __device__ __forceinline__ unsigned cvt_pk_bf16(float lo, float hi) { unsigned r; asm volatile("v_cvt_pk_bf16_f32 %0, %1, %2" : "=v"(r) : "v"(lo), "v"(hi)); return r; }
; __device__ __forceinline__ void wconv_item(const float* W, int K, int Norig, int Nphys, bf16_t* WT, const float* gA, const float* gB, int split, int mapid, LAS float* scr, int item, int lane) {
;     ...
;     for (int i = 0; i < 32; ++i) { const int kk = 2 * i + (lane >> 5), k = k0 + kk;
;         float v = wv[i];
;         if (gA) v *= (k < split ? gA[k] : gB[k - split]);
;         scr[kk * 33 + (lane & 31)] = v; }
;     asm volatile("s_waitcnt lgkmcnt(0)" ::: "memory");
;     const int c = lane & 7;
; #pragma unroll
;     for (int j = 0; j < 4; ++j) { const int n = (lane >> 3) + 8 * j; const LAS float* s = scr + (8 * c) * 33 + n;
;         u32x4 o; o.x = cvt_pk_bf16(s[0 * 33], s[1 * 33]); o.y = cvt_pk_bf16(s[2 * 33], s[3 * 33]); o.z = cvt_pk_bf16(s[4 * 33], s[5 * 33]); o.w = cvt_pk_bf16(s[6 * 33], s[7 * 33]);
;         *(u32x4*)(WT + (size_t)(n0 + n) * K + k0 + 8 * c) = o; }
;     asm volatile("s_waitcnt lgkmcnt(0)" ::: "memory");
	ds_write2_b32 v4, v106, v107 offset0:164 offset1:230
	v_add_u32_e32 v4, 0x1400, v45
	s_waitcnt vmcnt(10)
	ds_write2_b32 v4, v108, v109 offset0:40 offset1:106
	s_waitcnt vmcnt(8)
	ds_write2_b32 v4, v110, v38 offset0:172 offset1:238
	v_add_u32_e32 v4, 0x1800, v45
	s_waitcnt vmcnt(6)
	ds_write2_b32 v4, v24, v25 offset0:48 offset1:114
	s_waitcnt vmcnt(4)
	ds_write2_b32 v4, v26, v27 offset0:180 offset1:246
	v_add_u32_e32 v4, 0x1c00, v45
	s_waitcnt vmcnt(2)
	ds_write2_b32 v4, v28, v29 offset0:56 offset1:122
	s_waitcnt vmcnt(0)
	ds_write2_b32 v4, v30, v22 offset0:188 offset1:254
	s_waitcnt lgkmcnt(0)
	ds_read2_b32 v[22:23], v47 offset1:33
	s_waitcnt lgkmcnt(0)
	v_cvt_pk_bf16_f32 v22, v22, v23
	ds_read2_b32 v[24:25], v47 offset0:66 offset1:99
	v_or_b32_e32 v4, s4, v46
	s_waitcnt lgkmcnt(0)
	v_cvt_pk_bf16_f32 v23, v24, v25
	ds_read2_b32 v[24:25], v47 offset0:132 offset1:165
	v_lshl_add_u64 v[28:29], v[6:7], 0, s[34:35]
	v_lshlrev_b32_e32 v4, 9, v4
	s_waitcnt lgkmcnt(0)
	v_cvt_pk_bf16_f32 v24, v24, v25
	ds_read2_b32 v[26:27], v47 offset0:198 offset1:231
	s_waitcnt lgkmcnt(0)
	v_cvt_pk_bf16_f32 v25, v26, v27
	v_lshl_add_u64 v[30:31], v[28:29], 0, v[4:5]
	ds_read2_b32 v[26:27], v47 offset0:8 offset1:41
	global_store_dwordx4 v[30:31], v[22:25], off
	v_or_b32_e32 v4, s4, v48
	v_lshlrev_b32_e32 v4, 9, v4
	s_waitcnt lgkmcnt(0)
	v_cvt_pk_bf16_f32 v22, v26, v27
	ds_read2_b32 v[24:25], v47 offset0:74 offset1:107
	s_waitcnt lgkmcnt(0)
	v_cvt_pk_bf16_f32 v23, v24, v25
	ds_read2_b32 v[24:25], v47 offset0:140 offset1:173
	s_waitcnt lgkmcnt(0)
	v_cvt_pk_bf16_f32 v24, v24, v25
	ds_read2_b32 v[26:27], v47 offset0:206 offset1:239
	s_waitcnt lgkmcnt(0)
	v_cvt_pk_bf16_f32 v25, v26, v27
	v_lshl_add_u64 v[30:31], v[28:29], 0, v[4:5]
	ds_read2_b32 v[26:27], v47 offset0:16 offset1:49
	global_store_dwordx4 v[30:31], v[22:25], off
	v_or_b32_e32 v4, s4, v49
	v_lshlrev_b32_e32 v4, 9, v4
	s_waitcnt lgkmcnt(0)
	v_cvt_pk_bf16_f32 v22, v26, v27
	ds_read2_b32 v[24:25], v47 offset0:82 offset1:115
	s_waitcnt lgkmcnt(0)
	v_cvt_pk_bf16_f32 v23, v24, v25
	ds_read2_b32 v[24:25], v47 offset0:148 offset1:181
	s_waitcnt lgkmcnt(0)
	v_cvt_pk_bf16_f32 v24, v24, v25
	ds_read2_b32 v[26:27], v47 offset0:214 offset1:247
	s_waitcnt lgkmcnt(0)
	v_cvt_pk_bf16_f32 v25, v26, v27
	v_lshl_add_u64 v[30:31], v[28:29], 0, v[4:5]
	ds_read2_b32 v[26:27], v47 offset0:24 offset1:57
	global_store_dwordx4 v[30:31], v[22:25], off
	v_or_b32_e32 v4, s4, v50
	v_lshlrev_b32_e32 v4, 9, v4
	s_waitcnt lgkmcnt(0)
	v_cvt_pk_bf16_f32 v22, v26, v27
	ds_read2_b32 v[24:25], v47 offset0:90 offset1:123
	s_waitcnt lgkmcnt(0)
	v_cvt_pk_bf16_f32 v23, v24, v25
	ds_read2_b32 v[24:25], v47 offset0:156 offset1:189
	s_waitcnt lgkmcnt(0)
	v_cvt_pk_bf16_f32 v24, v24, v25
	ds_read2_b32 v[26:27], v47 offset0:222 offset1:255
	s_waitcnt lgkmcnt(0)
	v_cvt_pk_bf16_f32 v25, v26, v27
	v_lshl_add_u64 v[26:27], v[28:29], 0, v[4:5]
	global_store_dwordx4 v[26:27], v[22:25], off
	s_waitcnt lgkmcnt(0)
	s_mov_b64 s[4:5], 0
; __device__ __forceinline__ void wconv_item(const float* W, int K, int Norig, int Nphys, bf16_t* WT, const float* gA, const float* gB, int split, int mapid, LAS float* scr, int item, int lane) {
;     const int nblk = Nphys / 32, kb = item / nblk, nb = item % nblk, k0 = 64 * kb, n0 = 32 * nb;
;     const int norig = colmap(mapid, n0 + (lane & 31));
;     float wv[32];
; #pragma unroll
;     for (int i = 0; i < 32; ++i) { const int k = k0 + 2 * i + (lane >> 5); wv[i] = (norig >= 0) ? W[(size_t)k * Norig + norig] : 0.f; }
; #pragma unroll
;     for (int i = 0; i < 32; ++i) { const int kk = 2 * i + (lane >> 5), k = k0 + kk;
;         float v = wv[i];
;         if (gA) v *= (k < split ? gA[k] : gB[k - split]);
;         scr[kk * 33 + (lane & 31)] = v; }
.LBB0_20:
	s_andn2_b64 vcc, exec, s[4:5]
	s_cbranch_vccnz .LBB0_34
	s_add_i32 s4, s89, 0x400
	s_and_b32 s34, s4, 0x1ffc0
	s_add_i32 s4, s87, 0xfffd0e00
	s_and_b32 s82, s4, 0x3e0
	v_or_b32_e32 v4, s82, v1
	v_or_b32_e32 v38, s34, v2
	v_lshlrev_b32_e32 v4, 2, v4
	v_lshl_add_u64 v[22:23], s[22:23], 0, v[4:5]
	v_lshlrev_b32_e32 v4, 12, v38
	v_lshl_add_u64 v[22:23], v[22:23], 0, v[4:5]
	v_add_co_u32_e32 v24, vcc, 0x2000, v22
	v_cndmask_b32_e64 v39, 0, 1, s[40:41]
	s_nop 0
	v_addc_co_u32_e32 v25, vcc, 0, v23, vcc
	v_add_co_u32_e32 v26, vcc, 0x4000, v22
	v_cmp_ne_u32_e64 s[4:5], 1, v39
	s_nop 0
	v_addc_co_u32_e32 v27, vcc, 0, v23, vcc
	v_add_co_u32_e32 v28, vcc, 0x6000, v22
	v_add_lshl_u32 v102, s34, v2, 2
	s_nop 0
	v_addc_co_u32_e32 v29, vcc, 0, v23, vcc
	v_add_co_u32_e32 v30, vcc, 0x8000, v22
	s_nop 1
	v_addc_co_u32_e32 v31, vcc, 0, v23, vcc
	v_add_co_u32_e32 v32, vcc, 0xa000, v22
	s_nop 1
	v_addc_co_u32_e32 v33, vcc, 0, v23, vcc
	v_add_co_u32_e32 v34, vcc, 0xc000, v22
	s_nop 1
	v_addc_co_u32_e32 v35, vcc, 0, v23, vcc
	v_add_co_u32_e32 v40, vcc, 0xe000, v22
	s_nop 1
	v_addc_co_u32_e32 v41, vcc, 0, v23, vcc
	global_load_dword v104, v[22:23], off nt
	global_load_dword v103, v[24:25], off nt
	global_load_dword v105, v[26:27], off nt
	global_load_dword v106, v[28:29], off nt
	global_load_dword v36, v[30:31], off nt
	global_load_dword v37, v[32:33], off nt
	s_nop 0
	global_load_dword v34, v[34:35], off nt
	s_nop 0
	global_load_dword v35, v[40:41], off nt
	v_add_co_u32_e32 v24, vcc, 0x10000, v22
	s_nop 1
	v_addc_co_u32_e32 v25, vcc, 0, v23, vcc
	v_add_co_u32_e32 v26, vcc, 0x12000, v22
	s_nop 1
	v_addc_co_u32_e32 v27, vcc, 0, v23, vcc
	v_add_co_u32_e32 v28, vcc, 0x14000, v22
	s_nop 1
	v_addc_co_u32_e32 v29, vcc, 0, v23, vcc
	v_add_co_u32_e32 v30, vcc, 0x16000, v22
	s_nop 1
	v_addc_co_u32_e32 v31, vcc, 0, v23, vcc
	v_add_co_u32_e32 v32, vcc, 0x18000, v22
	s_nop 1
	v_addc_co_u32_e32 v33, vcc, 0, v23, vcc
	v_add_co_u32_e32 v40, vcc, 0x1a000, v22
	s_nop 1
	v_addc_co_u32_e32 v41, vcc, 0, v23, vcc
	v_add_co_u32_e32 v42, vcc, 0x1c000, v22
	s_nop 1
	v_addc_co_u32_e32 v43, vcc, 0, v23, vcc
	v_add_co_u32_e32 v94, vcc, 0x1e000, v22
	s_nop 1
	v_addc_co_u32_e32 v95, vcc, 0, v23, vcc
	global_load_dword v98, v[24:25], off nt
	global_load_dword v99, v[26:27], off nt
	global_load_dword v100, v[28:29], off nt
	global_load_dword v101, v[30:31], off nt
	s_nop 0
	global_load_dword v32, v[32:33], off nt
	s_nop 0
	global_load_dword v33, v[40:41], off nt
	global_load_dword v30, v[42:43], off nt
	global_load_dword v31, v[94:95], off nt
	v_add_co_u32_e32 v24, vcc, 0x20000, v22
	s_nop 1
	v_addc_co_u32_e32 v25, vcc, 0, v23, vcc
	v_add_co_u32_e32 v26, vcc, 0x22000, v22
	s_nop 1
	v_addc_co_u32_e32 v27, vcc, 0, v23, vcc
	v_add_co_u32_e32 v28, vcc, 0x24000, v22
	s_nop 1
	v_addc_co_u32_e32 v29, vcc, 0, v23, vcc
	v_add_co_u32_e32 v40, vcc, 0x26000, v22
	s_nop 1
	v_addc_co_u32_e32 v41, vcc, 0, v23, vcc
	v_add_co_u32_e32 v42, vcc, 0x28000, v22
	s_nop 1
	v_addc_co_u32_e32 v43, vcc, 0, v23, vcc
	v_add_co_u32_e32 v108, vcc, 0x2a000, v22
	s_nop 1
	v_addc_co_u32_e32 v109, vcc, 0, v23, vcc
	v_add_co_u32_e32 v110, vcc, 0x2c000, v22
	s_nop 1
	v_addc_co_u32_e32 v111, vcc, 0, v23, vcc
	v_add_co_u32_e32 v112, vcc, 0x2e000, v22
	s_nop 1
	v_addc_co_u32_e32 v113, vcc, 0, v23, vcc
	global_load_dword v94, v[24:25], off nt
	global_load_dword v95, v[26:27], off nt
	global_load_dword v96, v[28:29], off nt
	global_load_dword v97, v[40:41], off nt
	s_nop 0
	global_load_dword v28, v[42:43], off nt
	global_load_dword v29, v[108:109], off nt
	global_load_dword v26, v[110:111], off nt
	global_load_dword v27, v[112:113], off nt
	v_add_co_u32_e32 v24, vcc, 0x30000, v22
	s_nop 1
	v_addc_co_u32_e32 v25, vcc, 0, v23, vcc
	v_add_co_u32_e32 v40, vcc, 0x32000, v22
	s_nop 1
	v_addc_co_u32_e32 v41, vcc, 0, v23, vcc
	v_add_co_u32_e32 v108, vcc, 0x34000, v22
	s_nop 1
	v_addc_co_u32_e32 v109, vcc, 0, v23, vcc
	v_add_co_u32_e32 v110, vcc, 0x36000, v22
	s_nop 1
	v_addc_co_u32_e32 v111, vcc, 0, v23, vcc
	v_add_co_u32_e32 v112, vcc, 0x38000, v22
	s_nop 1
	v_addc_co_u32_e32 v113, vcc, 0, v23, vcc
	v_add_co_u32_e32 v114, vcc, 0x3a000, v22
	s_nop 1
	v_addc_co_u32_e32 v115, vcc, 0, v23, vcc
	v_add_co_u32_e32 v116, vcc, 0x3c000, v22
	s_nop 1
	v_addc_co_u32_e32 v117, vcc, 0, v23, vcc
	v_add_co_u32_e32 v118, vcc, 0x3e000, v22
	s_nop 1
	v_addc_co_u32_e32 v119, vcc, 0, v23, vcc
	global_load_dword v4, v[24:25], off nt
	global_load_dword v42, v[40:41], off nt
	global_load_dword v43, v[108:109], off nt
	global_load_dword v93, v[110:111], off nt
	s_nop 0
	global_load_dword v24, v[112:113], off nt
	global_load_dword v25, v[114:115], off nt
	global_load_dword v22, v[116:117], off nt
	global_load_dword v23, v[118:119], off nt
	s_andn2_b64 vcc, exec, s[40:41]
	s_cbranch_vccnz .LBB0_210
	v_lshlrev_b32_e32 v107, 2, v38
	global_load_dword v108, v102, s[20:21] offset:8
	global_load_dword v109, v102, s[20:21] offset:16
	global_load_dword v110, v102, s[20:21] offset:24
	global_load_dword v38, v102, s[20:21] offset:32
	global_load_dword v39, v102, s[20:21] offset:40
	global_load_dword v40, v102, s[20:21] offset:48
	global_load_dword v41, v102, s[20:21] offset:56
	s_nop 0
	global_load_dword v107, v107, s[20:21]
	v_add_u32_e32 v111, v44, v52
	s_waitcnt vmcnt(7)
	v_mul_f32_e32 v108, v103, v108
	s_waitcnt vmcnt(6)
	v_mul_f32_e32 v109, v105, v109
	s_waitcnt vmcnt(5)
	v_mul_f32_e32 v110, v106, v110
	s_waitcnt vmcnt(3)
	v_pk_mul_f32 v[38:39], v[36:37], v[38:39]
	s_waitcnt vmcnt(1)
	v_pk_mul_f32 v[40:41], v[34:35], v[40:41]
	s_waitcnt vmcnt(0)
	v_mul_f32_e32 v107, v104, v107
	ds_write_b32 v45, v107
	ds_write2_b32 v111, v108, v109 offset1:66
	ds_write_b32 v111, v110 offset:528
	s_cbranch_execnz .LBB0_24

; __device__ __forceinline__ void wconv_item(const float* W, int K, int Norig, int Nphys, bf16_t* WT, const float* gA, const float* gB, int split, int mapid, LAS float* scr, int item, int lane) {
;     const int nblk = Nphys / 32, kb = item / nblk, nb = item % nblk, k0 = 64 * kb, n0 = 32 * nb;
;     const int norig = colmap(mapid, n0 + (lane & 31));
;     float wv[32];
; #pragma unroll
;     for (int i = 0; i < 32; ++i) { const int k = k0 + 2 * i + (lane >> 5); wv[i] = (norig >= 0) ? W[(size_t)k * Norig + norig] : 0.f; }
; #pragma unroll
;     for (int i = 0; i < 32; ++i) { const int kk = 2 * i + (lane >> 5), k = k0 + kk;
;         float v = wv[i];
;         if (gA) v *= (k < split ? gA[k] : gB[k - split]);
;         scr[kk * 33 + (lane & 31)] = v; }
.LBB0_35:
	s_andn2_b64 vcc, exec, s[4:5]
	s_cbranch_vccnz .LBB0_37
	s_add_i32 s4, s89, 0x1400
	s_and_b32 s5, s4, 0x1ffc0
	s_add_i32 s4, s87, 0xfffe0e00
	s_and_b32 s4, s4, 0x3e0
	v_or_b32_e32 v4, s4, v1
	v_or_b32_e32 v24, s5, v2
	v_lshlrev_b32_e32 v4, 2, v4
	v_lshl_add_u64 v[22:23], s[18:19], 0, v[4:5]
	v_lshlrev_b32_e32 v4, 12, v24
	v_lshl_add_u64 v[22:23], v[22:23], 0, v[4:5]
	v_add_co_u32_e32 v24, vcc, 0x2000, v22
	s_lshl_b32 s34, s5, 1
	s_nop 0
	v_addc_co_u32_e32 v25, vcc, 0, v23, vcc
	v_add_co_u32_e32 v26, vcc, 0x4000, v22
	s_nop 1
	v_addc_co_u32_e32 v27, vcc, 0, v23, vcc
	v_add_co_u32_e32 v28, vcc, 0x6000, v22
	s_nop 1
	v_addc_co_u32_e32 v29, vcc, 0, v23, vcc
	v_add_co_u32_e32 v30, vcc, 0x8000, v22
	s_nop 1
	v_addc_co_u32_e32 v31, vcc, 0, v23, vcc
	v_add_co_u32_e32 v32, vcc, 0xa000, v22
	s_nop 1
	v_addc_co_u32_e32 v33, vcc, 0, v23, vcc
	v_add_co_u32_e32 v34, vcc, 0xc000, v22
	s_nop 1
	v_addc_co_u32_e32 v35, vcc, 0, v23, vcc
	v_add_co_u32_e32 v36, vcc, 0xe000, v22
	s_nop 1
	v_addc_co_u32_e32 v37, vcc, 0, v23, vcc
	global_load_dword v4, v[22:23], off nt
	global_load_dword v40, v[24:25], off nt
	global_load_dword v41, v[26:27], off nt
	global_load_dword v42, v[28:29], off nt
	global_load_dword v43, v[30:31], off nt
	global_load_dword v93, v[32:33], off nt
	global_load_dword v94, v[34:35], off nt
	global_load_dword v95, v[36:37], off nt
	v_add_co_u32_e32 v24, vcc, 0x10000, v22
	s_nop 1
	v_addc_co_u32_e32 v25, vcc, 0, v23, vcc
	v_add_co_u32_e32 v26, vcc, 0x12000, v22
	s_nop 1
	v_addc_co_u32_e32 v27, vcc, 0, v23, vcc
	v_add_co_u32_e32 v28, vcc, 0x14000, v22
	s_nop 1
	v_addc_co_u32_e32 v29, vcc, 0, v23, vcc
	v_add_co_u32_e32 v30, vcc, 0x16000, v22
	s_nop 1
	v_addc_co_u32_e32 v31, vcc, 0, v23, vcc
	v_add_co_u32_e32 v32, vcc, 0x18000, v22
	s_nop 1
	v_addc_co_u32_e32 v33, vcc, 0, v23, vcc
	v_add_co_u32_e32 v34, vcc, 0x1a000, v22
	s_nop 1
	v_addc_co_u32_e32 v35, vcc, 0, v23, vcc
	v_add_co_u32_e32 v36, vcc, 0x1c000, v22
	s_nop 1
	v_addc_co_u32_e32 v37, vcc, 0, v23, vcc
	v_add_co_u32_e32 v38, vcc, 0x1e000, v22
	s_nop 1
	v_addc_co_u32_e32 v39, vcc, 0, v23, vcc
	global_load_dword v96, v[24:25], off nt
	global_load_dword v97, v[26:27], off nt
	global_load_dword v98, v[28:29], off nt
	global_load_dword v99, v[30:31], off nt
	global_load_dword v100, v[32:33], off nt
	global_load_dword v101, v[34:35], off nt
	global_load_dword v102, v[36:37], off nt
	global_load_dword v103, v[38:39], off nt
	v_add_co_u32_e32 v24, vcc, 0x20000, v22
	s_nop 1
	v_addc_co_u32_e32 v25, vcc, 0, v23, vcc
	v_add_co_u32_e32 v26, vcc, 0x22000, v22
	s_nop 1
	v_addc_co_u32_e32 v27, vcc, 0, v23, vcc
	v_add_co_u32_e32 v28, vcc, 0x24000, v22
	s_nop 1
	v_addc_co_u32_e32 v29, vcc, 0, v23, vcc
	v_add_co_u32_e32 v30, vcc, 0x26000, v22
	s_nop 1
	v_addc_co_u32_e32 v31, vcc, 0, v23, vcc
	v_add_co_u32_e32 v32, vcc, 0x28000, v22
	s_nop 1
	v_addc_co_u32_e32 v33, vcc, 0, v23, vcc
	v_add_co_u32_e32 v34, vcc, 0x2a000, v22
	s_nop 1
	v_addc_co_u32_e32 v35, vcc, 0, v23, vcc
	v_add_co_u32_e32 v36, vcc, 0x2c000, v22
	s_nop 1
	v_addc_co_u32_e32 v37, vcc, 0, v23, vcc
	v_add_co_u32_e32 v38, vcc, 0x2e000, v22
	s_nop 1
	v_addc_co_u32_e32 v39, vcc, 0, v23, vcc
	global_load_dword v104, v[24:25], off nt
	global_load_dword v105, v[26:27], off nt
	global_load_dword v106, v[28:29], off nt
	global_load_dword v107, v[30:31], off nt
	global_load_dword v108, v[32:33], off nt
	global_load_dword v109, v[34:35], off nt
	global_load_dword v110, v[36:37], off nt
	s_nop 0
	global_load_dword v38, v[38:39], off nt
	v_add_co_u32_e32 v24, vcc, 0x30000, v22
	s_nop 1
	v_addc_co_u32_e32 v25, vcc, 0, v23, vcc
	v_add_co_u32_e32 v26, vcc, 0x32000, v22
	s_nop 1
	v_addc_co_u32_e32 v27, vcc, 0, v23, vcc
	v_add_co_u32_e32 v28, vcc, 0x34000, v22
	s_nop 1
	v_addc_co_u32_e32 v29, vcc, 0, v23, vcc
	v_add_co_u32_e32 v30, vcc, 0x36000, v22
	s_nop 1
	v_addc_co_u32_e32 v31, vcc, 0, v23, vcc
	v_add_co_u32_e32 v32, vcc, 0x38000, v22
	s_nop 1
	v_addc_co_u32_e32 v33, vcc, 0, v23, vcc
	v_add_co_u32_e32 v34, vcc, 0x3a000, v22
	s_nop 1
	v_addc_co_u32_e32 v35, vcc, 0, v23, vcc
	v_add_co_u32_e32 v36, vcc, 0x3c000, v22
	s_nop 1
	v_addc_co_u32_e32 v37, vcc, 0, v23, vcc
	v_add_co_u32_e32 v22, vcc, 0x3e000, v22
	s_nop 1
	v_addc_co_u32_e32 v23, vcc, 0, v23, vcc
	global_load_dword v24, v[24:25], off nt
	s_nop 0
	global_load_dword v25, v[26:27], off nt
	s_nop 0
	global_load_dword v26, v[28:29], off nt
	global_load_dword v27, v[30:31], off nt
	s_nop 0
	global_load_dword v28, v[32:33], off nt
	global_load_dword v29, v[34:35], off nt
	global_load_dword v30, v[36:37], off nt
	s_nop 0
	global_load_dword v22, v[22:23], off nt
	s_waitcnt vmcnt(30)
; #define LAS __attribute__((address_space(3)))
; __device__ __forceinline__ unsigned cvt_pk_bf16(float lo, float hi) { unsigned r; asm volatile("v_cvt_pk_bf16_f32 %0, %1, %2" : "=v"(r) : "v"(lo), "v"(hi)); return r; }
; __device__ __forceinline__ void wconv_item(const float* W, int K, int Norig, int Nphys, bf16_t* WT, const float* gA, const float* gB, int split, int mapid, LAS float* scr, int item, int lane) {
;     ...
;     for (int i = 0; i < 32; ++i) { const int kk = 2 * i + (lane >> 5), k = k0 + kk;
;         float v = wv[i];
;         if (gA) v *= (k < split ? gA[k] : gB[k - split]);
;         scr[kk * 33 + (lane & 31)] = v; }
;     asm volatile("s_waitcnt lgkmcnt(0)" ::: "memory");
;     const int c = lane & 7;
; #pragma unroll
;     for (int j = 0; j < 4; ++j) { const int n = (lane >> 3) + 8 * j; const LAS float* s = scr + (8 * c) * 33 + n;
;         u32x4 o; o.x = cvt_pk_bf16(s[0 * 33], s[1 * 33]); o.y = cvt_pk_bf16(s[2 * 33], s[3 * 33]); o.z = cvt_pk_bf16(s[4 * 33], s[5 * 33]); o.w = cvt_pk_bf16(s[6 * 33], s[7 * 33]);
;         *(u32x4*)(WT + (size_t)(n0 + n) * K + k0 + 8 * c) = o; }
;     asm volatile("s_waitcnt lgkmcnt(0)" ::: "memory");
	ds_write2_b32 v45, v4, v40 offset1:66
	s_waitcnt vmcnt(28)
	ds_write2_b32 v45, v41, v42 offset0:132 offset1:198
	v_add_u32_e32 v4, 0x400, v45
	s_waitcnt vmcnt(26)
	ds_write2_b32 v4, v43, v93 offset0:8 offset1:74
	s_waitcnt vmcnt(24)
	ds_write2_b32 v4, v94, v95 offset0:140 offset1:206
	v_add_u32_e32 v4, 0x800, v45
	s_waitcnt vmcnt(22)
	ds_write2_b32 v4, v96, v97 offset0:16 offset1:82
	s_waitcnt vmcnt(20)
	ds_write2_b32 v4, v98, v99 offset0:148 offset1:214
	v_add_u32_e32 v4, 0xc00, v45
	s_waitcnt vmcnt(18)
	ds_write2_b32 v4, v100, v101 offset0:24 offset1:90
	s_waitcnt vmcnt(16)
	ds_write2_b32 v4, v102, v103 offset0:156 offset1:222
	v_add_u32_e32 v4, 0x1000, v45
	s_waitcnt vmcnt(14)
	ds_write2_b32 v4, v104, v105 offset0:32 offset1:98
	s_waitcnt vmcnt(12)
	ds_write2_b32 v4, v106, v107 offset0:164 offset1:230
	v_add_u32_e32 v4, 0x1400, v45
	s_waitcnt vmcnt(10)
	ds_write2_b32 v4, v108, v109 offset0:40 offset1:106
	s_waitcnt vmcnt(8)
	ds_write2_b32 v4, v110, v38 offset0:172 offset1:238
	v_add_u32_e32 v4, 0x1800, v45
	s_waitcnt vmcnt(6)
	ds_write2_b32 v4, v24, v25 offset0:48 offset1:114
	s_waitcnt vmcnt(4)
	ds_write2_b32 v4, v26, v27 offset0:180 offset1:246
	v_add_u32_e32 v4, 0x1c00, v45
	s_waitcnt vmcnt(2)
	ds_write2_b32 v4, v28, v29 offset0:56 offset1:122
	s_waitcnt vmcnt(0)
	ds_write2_b32 v4, v30, v22 offset0:188 offset1:254
	s_waitcnt lgkmcnt(0)
	ds_read2_b32 v[22:23], v47 offset1:33
	s_waitcnt lgkmcnt(0)
	v_cvt_pk_bf16_f32 v22, v22, v23
	ds_read2_b32 v[24:25], v47 offset0:66 offset1:99
	v_or_b32_e32 v4, s4, v46
	s_waitcnt lgkmcnt(0)
	v_cvt_pk_bf16_f32 v23, v24, v25
	ds_read2_b32 v[24:25], v47 offset0:132 offset1:165
	v_lshl_add_u64 v[28:29], v[10:11], 0, s[34:35]
	v_lshlrev_b32_e32 v4, 13, v4
	s_waitcnt lgkmcnt(0)
	v_cvt_pk_bf16_f32 v24, v24, v25
	ds_read2_b32 v[26:27], v47 offset0:198 offset1:231
	s_waitcnt lgkmcnt(0)
	v_cvt_pk_bf16_f32 v25, v26, v27
	v_lshl_add_u64 v[30:31], v[28:29], 0, v[4:5]
	ds_read2_b32 v[26:27], v47 offset0:8 offset1:41
	global_store_dwordx4 v[30:31], v[22:25], off
	v_or_b32_e32 v4, s4, v48
	v_lshlrev_b32_e32 v4, 13, v4
	s_waitcnt lgkmcnt(0)
	v_cvt_pk_bf16_f32 v22, v26, v27
	ds_read2_b32 v[24:25], v47 offset0:74 offset1:107
	s_waitcnt lgkmcnt(0)
	v_cvt_pk_bf16_f32 v23, v24, v25
	ds_read2_b32 v[24:25], v47 offset0:140 offset1:173
	s_waitcnt lgkmcnt(0)
	v_cvt_pk_bf16_f32 v24, v24, v25
	ds_read2_b32 v[26:27], v47 offset0:206 offset1:239
	s_waitcnt lgkmcnt(0)
	v_cvt_pk_bf16_f32 v25, v26, v27
	v_lshl_add_u64 v[30:31], v[28:29], 0, v[4:5]
	ds_read2_b32 v[26:27], v47 offset0:16 offset1:49
	global_store_dwordx4 v[30:31], v[22:25], off
	v_or_b32_e32 v4, s4, v49
	v_lshlrev_b32_e32 v4, 13, v4
	s_waitcnt lgkmcnt(0)
	v_cvt_pk_bf16_f32 v22, v26, v27
	ds_read2_b32 v[24:25], v47 offset0:82 offset1:115
	s_waitcnt lgkmcnt(0)
	v_cvt_pk_bf16_f32 v23, v24, v25
	ds_read2_b32 v[24:25], v47 offset0:148 offset1:181
	s_waitcnt lgkmcnt(0)
	v_cvt_pk_bf16_f32 v24, v24, v25
	ds_read2_b32 v[26:27], v47 offset0:214 offset1:247
	s_waitcnt lgkmcnt(0)
	v_cvt_pk_bf16_f32 v25, v26, v27
	v_lshl_add_u64 v[30:31], v[28:29], 0, v[4:5]
	ds_read2_b32 v[26:27], v47 offset0:24 offset1:57
	global_store_dwordx4 v[30:31], v[22:25], off
	v_or_b32_e32 v4, s4, v50
	v_lshlrev_b32_e32 v4, 13, v4
	s_waitcnt lgkmcnt(0)
	v_cvt_pk_bf16_f32 v22, v26, v27
	ds_read2_b32 v[24:25], v47 offset0:90 offset1:123
	s_waitcnt lgkmcnt(0)
	v_cvt_pk_bf16_f32 v23, v24, v25
	ds_read2_b32 v[24:25], v47 offset0:156 offset1:189
	s_waitcnt lgkmcnt(0)
	v_cvt_pk_bf16_f32 v24, v24, v25
	ds_read2_b32 v[26:27], v47 offset0:222 offset1:255
	s_waitcnt lgkmcnt(0)
	v_cvt_pk_bf16_f32 v25, v26, v27
	v_lshl_add_u64 v[26:27], v[28:29], 0, v[4:5]
	global_store_dwordx4 v[26:27], v[22:25], off
	s_waitcnt lgkmcnt(0)

; __device__ __forceinline__ void wconv_item(const float* W, int K, int Norig, int Nphys, bf16_t* WT, const float* gA, const float* gB, int split, int mapid, LAS float* scr, int item, int lane) {
;     const int nblk = Nphys / 32, kb = item / nblk, nb = item % nblk, k0 = 64 * kb, n0 = 32 * nb;
;     const int norig = colmap(mapid, n0 + (lane & 31));
;     float wv[32];
; #pragma unroll
;     for (int i = 0; i < 32; ++i) { const int k = k0 + 2 * i + (lane >> 5); wv[i] = (norig >= 0) ? W[(size_t)k * Norig + norig] : 0.f; }
; #pragma unroll
;     for (int i = 0; i < 32; ++i) { const int kk = 2 * i + (lane >> 5), k = k0 + kk;
;         float v = wv[i];
;         if (gA) v *= (k < split ? gA[k] : gB[k - split]);
;         scr[kk * 33 + (lane & 31)] = v; }
.LBB0_38:
	s_andn2_b64 vcc, exec, s[4:5]
	s_cbranch_vccnz .LBB0_52
	s_add_i32 s4, s74, 0xfffff870
	s_lshr_b32 s4, s4, 1
	s_and_b32 s34, s4, 0x7fc0
	s_add_i32 s4, s87, 0xffff0e00
	s_and_b32 s82, s4, 0xfe0
	v_or_b32_e32 v4, s82, v1
	v_or_b32_e32 v38, s34, v2
	v_lshlrev_b32_e32 v4, 2, v4
	v_lshl_add_u64 v[22:23], s[16:17], 0, v[4:5]
	v_lshlrev_b32_e32 v4, 14, v38
	v_lshl_add_u64 v[22:23], v[22:23], 0, v[4:5]
	v_add_co_u32_e32 v24, vcc, 0x8000, v22
	v_cndmask_b32_e64 v39, 0, 1, s[42:43]
	s_nop 0
	v_addc_co_u32_e32 v25, vcc, 0, v23, vcc
	v_add_co_u32_e32 v26, vcc, 0x10000, v22
	v_cmp_ne_u32_e64 s[4:5], 1, v39
	s_nop 0
	v_addc_co_u32_e32 v27, vcc, 0, v23, vcc
	v_add_co_u32_e32 v28, vcc, 0x18000, v22
	v_add_lshl_u32 v102, s34, v2, 2
	s_nop 0
	v_addc_co_u32_e32 v29, vcc, 0, v23, vcc
	v_add_co_u32_e32 v30, vcc, 0x20000, v22
	s_nop 1
	v_addc_co_u32_e32 v31, vcc, 0, v23, vcc
	v_add_co_u32_e32 v32, vcc, 0x28000, v22
	s_nop 1
	v_addc_co_u32_e32 v33, vcc, 0, v23, vcc
	v_add_co_u32_e32 v34, vcc, 0x30000, v22
	s_nop 1
	v_addc_co_u32_e32 v35, vcc, 0, v23, vcc
	v_add_co_u32_e32 v40, vcc, 0x38000, v22
	s_nop 1
	v_addc_co_u32_e32 v41, vcc, 0, v23, vcc
	global_load_dword v104, v[22:23], off nt
	global_load_dword v103, v[24:25], off nt
	global_load_dword v105, v[26:27], off nt
	global_load_dword v106, v[28:29], off nt
	global_load_dword v36, v[30:31], off nt
	global_load_dword v37, v[32:33], off nt
	s_nop 0
	global_load_dword v34, v[34:35], off nt
	s_nop 0
	global_load_dword v35, v[40:41], off nt
	v_add_co_u32_e32 v24, vcc, 0x40000, v22
	s_nop 1
	v_addc_co_u32_e32 v25, vcc, 0, v23, vcc
	v_add_co_u32_e32 v26, vcc, 0x48000, v22
	s_nop 1
	v_addc_co_u32_e32 v27, vcc, 0, v23, vcc
	v_add_co_u32_e32 v28, vcc, 0x50000, v22
	s_nop 1
	v_addc_co_u32_e32 v29, vcc, 0, v23, vcc
	v_add_co_u32_e32 v30, vcc, 0x58000, v22
	s_nop 1
	v_addc_co_u32_e32 v31, vcc, 0, v23, vcc
	v_add_co_u32_e32 v32, vcc, 0x60000, v22
	s_nop 1
	v_addc_co_u32_e32 v33, vcc, 0, v23, vcc
	v_add_co_u32_e32 v40, vcc, 0x68000, v22
	s_nop 1
	v_addc_co_u32_e32 v41, vcc, 0, v23, vcc
	v_add_co_u32_e32 v42, vcc, 0x70000, v22
	s_nop 1
	v_addc_co_u32_e32 v43, vcc, 0, v23, vcc
	v_add_co_u32_e32 v94, vcc, 0x78000, v22
	s_nop 1
	v_addc_co_u32_e32 v95, vcc, 0, v23, vcc
	global_load_dword v98, v[24:25], off nt
	global_load_dword v99, v[26:27], off nt
	global_load_dword v100, v[28:29], off nt
	global_load_dword v101, v[30:31], off nt
	s_nop 0
	global_load_dword v32, v[32:33], off nt
	s_nop 0
	global_load_dword v33, v[40:41], off nt
	global_load_dword v30, v[42:43], off nt
	global_load_dword v31, v[94:95], off nt
	v_add_co_u32_e32 v24, vcc, 0x80000, v22
	s_nop 1
	v_addc_co_u32_e32 v25, vcc, 0, v23, vcc
	v_add_co_u32_e32 v26, vcc, 0x88000, v22
	s_nop 1
	v_addc_co_u32_e32 v27, vcc, 0, v23, vcc
	v_add_co_u32_e32 v28, vcc, 0x90000, v22
	s_nop 1
	v_addc_co_u32_e32 v29, vcc, 0, v23, vcc
	v_add_co_u32_e32 v40, vcc, 0x98000, v22
	s_nop 1
	v_addc_co_u32_e32 v41, vcc, 0, v23, vcc
	v_add_co_u32_e32 v42, vcc, 0xa0000, v22
	s_nop 1
	v_addc_co_u32_e32 v43, vcc, 0, v23, vcc
	v_add_co_u32_e32 v108, vcc, 0xa8000, v22
	s_nop 1
	v_addc_co_u32_e32 v109, vcc, 0, v23, vcc
	v_add_co_u32_e32 v110, vcc, 0xb0000, v22
	s_nop 1
	v_addc_co_u32_e32 v111, vcc, 0, v23, vcc
	v_add_co_u32_e32 v112, vcc, 0xb8000, v22
	s_nop 1
	v_addc_co_u32_e32 v113, vcc, 0, v23, vcc
	global_load_dword v94, v[24:25], off nt
	global_load_dword v95, v[26:27], off nt
	global_load_dword v96, v[28:29], off nt
	global_load_dword v97, v[40:41], off nt
	s_nop 0
	global_load_dword v28, v[42:43], off nt
	global_load_dword v29, v[108:109], off nt
	global_load_dword v26, v[110:111], off nt
	global_load_dword v27, v[112:113], off nt
	v_add_co_u32_e32 v24, vcc, 0xc0000, v22
	s_nop 1
	v_addc_co_u32_e32 v25, vcc, 0, v23, vcc
	v_add_co_u32_e32 v40, vcc, 0xc8000, v22
	s_nop 1
	v_addc_co_u32_e32 v41, vcc, 0, v23, vcc
	v_add_co_u32_e32 v108, vcc, 0xd0000, v22
	s_nop 1
	v_addc_co_u32_e32 v109, vcc, 0, v23, vcc
	v_add_co_u32_e32 v110, vcc, 0xd8000, v22
	s_nop 1
	v_addc_co_u32_e32 v111, vcc, 0, v23, vcc
	v_add_co_u32_e32 v112, vcc, 0xe0000, v22
	s_nop 1
	v_addc_co_u32_e32 v113, vcc, 0, v23, vcc
	v_add_co_u32_e32 v114, vcc, 0xe8000, v22
	s_nop 1
	v_addc_co_u32_e32 v115, vcc, 0, v23, vcc
	v_add_co_u32_e32 v116, vcc, 0xf0000, v22
	s_nop 1
	v_addc_co_u32_e32 v117, vcc, 0, v23, vcc
	v_add_co_u32_e32 v118, vcc, 0xf8000, v22
	s_nop 1
	v_addc_co_u32_e32 v119, vcc, 0, v23, vcc
	global_load_dword v4, v[24:25], off nt
	global_load_dword v42, v[40:41], off nt
	global_load_dword v43, v[108:109], off nt
	global_load_dword v93, v[110:111], off nt
	s_nop 0
	global_load_dword v24, v[112:113], off nt
	global_load_dword v25, v[114:115], off nt
	global_load_dword v22, v[116:117], off nt
	global_load_dword v23, v[118:119], off nt
	s_andn2_b64 vcc, exec, s[42:43]
	s_cbranch_vccnz .LBB0_206
	v_lshlrev_b32_e32 v107, 2, v38
	global_load_dword v108, v102, s[14:15] offset:8
	global_load_dword v109, v102, s[14:15] offset:16
	global_load_dword v110, v102, s[14:15] offset:24
	global_load_dword v38, v102, s[14:15] offset:32
	global_load_dword v39, v102, s[14:15] offset:40
	global_load_dword v40, v102, s[14:15] offset:48
	global_load_dword v41, v102, s[14:15] offset:56
	s_nop 0
	global_load_dword v107, v107, s[14:15]
	v_add_u32_e32 v111, v44, v52
	s_waitcnt vmcnt(7)
	v_mul_f32_e32 v108, v103, v108
	s_waitcnt vmcnt(6)
	v_mul_f32_e32 v109, v105, v109
	s_waitcnt vmcnt(5)
	v_mul_f32_e32 v110, v106, v110
	s_waitcnt vmcnt(3)
	v_pk_mul_f32 v[38:39], v[36:37], v[38:39]
	s_waitcnt vmcnt(1)
	v_pk_mul_f32 v[40:41], v[34:35], v[40:41]
	s_waitcnt vmcnt(0)
	v_mul_f32_e32 v107, v104, v107
	ds_write_b32 v45, v107
	ds_write2_b32 v111, v108, v109 offset1:66
	ds_write_b32 v111, v110 offset:528
	s_cbranch_execnz .LBB0_42

; __device__ __forceinline__ void wconv_item(const float* W, int K, int Norig, int Nphys, bf16_t* WT, const float* gA, const float* gB, int split, int mapid, LAS float* scr, int item, int lane) {
;     const int nblk = Nphys / 32, kb = item / nblk, nb = item % nblk, k0 = 64 * kb, n0 = 32 * nb;
;     const int norig = colmap(mapid, n0 + (lane & 31));
;     float wv[32];
; #pragma unroll
;     for (int i = 0; i < 32; ++i) { const int k = k0 + 2 * i + (lane >> 5); wv[i] = (norig >= 0) ? W[(size_t)k * Norig + norig] : 0.f; }
; #pragma unroll
;     for (int i = 0; i < 32; ++i) { const int kk = 2 * i + (lane >> 5), k = k0 + kk;
;         float v = wv[i];
;         if (gA) v *= (k < split ? gA[k] : gB[k - split]);
;         scr[kk * 33 + (lane & 31)] = v; }
.LBB0_53:
	s_andn2_b64 vcc, exec, s[4:5]
	s_cbranch_vccnz .LBB0_67
	s_add_i32 s4, s89, 0x2800
	s_and_b32 s34, s4, 0x1ffc0
	s_add_i32 s4, s87, 0xffff4e00
	s_and_b32 s82, s4, 0x3e0
	v_or_b32_e32 v4, s82, v1
	v_or_b32_e32 v31, s34, v2
	v_lshlrev_b32_e32 v4, 2, v4
	v_lshl_add_u64 v[22:23], s[12:13], 0, v[4:5]
	v_lshlrev_b32_e32 v4, 12, v31
	v_lshl_add_u64 v[22:23], v[22:23], 0, v[4:5]
	v_add_co_u32_e32 v24, vcc, 0x2000, v22
	v_cndmask_b32_e64 v4, 0, 1, s[44:45]
	s_nop 0
	v_addc_co_u32_e32 v25, vcc, 0, v23, vcc
	v_add_co_u32_e32 v26, vcc, 0x4000, v22
	v_cmp_ne_u32_e64 s[4:5], 1, v4
	s_nop 0
	v_addc_co_u32_e32 v27, vcc, 0, v23, vcc
	v_add_co_u32_e32 v28, vcc, 0x6000, v22
	v_add_lshl_u32 v30, s34, v2, 2
	s_nop 0
	v_addc_co_u32_e32 v29, vcc, 0, v23, vcc
	v_add_co_u32_e32 v32, vcc, 0x8000, v22
	s_nop 1
	v_addc_co_u32_e32 v33, vcc, 0, v23, vcc
	v_add_co_u32_e32 v34, vcc, 0xa000, v22
	s_nop 1
	v_addc_co_u32_e32 v35, vcc, 0, v23, vcc
	v_add_co_u32_e32 v36, vcc, 0xc000, v22
	s_nop 1
	v_addc_co_u32_e32 v37, vcc, 0, v23, vcc
	v_add_co_u32_e32 v40, vcc, 0xe000, v22
	s_nop 1
	v_addc_co_u32_e32 v41, vcc, 0, v23, vcc
	global_load_dword v106, v[22:23], off nt
	global_load_dword v105, v[24:25], off nt
	global_load_dword v107, v[26:27], off nt
	global_load_dword v108, v[28:29], off nt
	global_load_dword v38, v[32:33], off nt
	global_load_dword v39, v[34:35], off nt
	s_nop 0
	global_load_dword v36, v[36:37], off nt
	s_nop 0
	global_load_dword v37, v[40:41], off nt
	v_add_co_u32_e32 v24, vcc, 0x10000, v22
	s_nop 1
	v_addc_co_u32_e32 v25, vcc, 0, v23, vcc
	v_add_co_u32_e32 v26, vcc, 0x12000, v22
	s_nop 1
	v_addc_co_u32_e32 v27, vcc, 0, v23, vcc
	v_add_co_u32_e32 v28, vcc, 0x14000, v22
	s_nop 1
	v_addc_co_u32_e32 v29, vcc, 0, v23, vcc
	v_add_co_u32_e32 v32, vcc, 0x16000, v22
	s_nop 1
	v_addc_co_u32_e32 v33, vcc, 0, v23, vcc
	v_add_co_u32_e32 v34, vcc, 0x18000, v22
	s_nop 1
	v_addc_co_u32_e32 v35, vcc, 0, v23, vcc
	v_add_co_u32_e32 v40, vcc, 0x1a000, v22
	s_nop 1
	v_addc_co_u32_e32 v41, vcc, 0, v23, vcc
	v_add_co_u32_e32 v42, vcc, 0x1c000, v22
	s_nop 1
	v_addc_co_u32_e32 v43, vcc, 0, v23, vcc
	v_add_co_u32_e32 v94, vcc, 0x1e000, v22
	s_nop 1
	v_addc_co_u32_e32 v95, vcc, 0, v23, vcc
	global_load_dword v101, v[24:25], off nt
	global_load_dword v102, v[26:27], off nt
	global_load_dword v103, v[28:29], off nt
	global_load_dword v104, v[32:33], off nt
	s_nop 0
	global_load_dword v34, v[34:35], off nt
	s_nop 0
	global_load_dword v35, v[40:41], off nt
	global_load_dword v32, v[42:43], off nt
	global_load_dword v33, v[94:95], off nt
	v_add_co_u32_e32 v24, vcc, 0x20000, v22
	s_nop 1
	v_addc_co_u32_e32 v25, vcc, 0, v23, vcc
	v_add_co_u32_e32 v26, vcc, 0x22000, v22
	s_nop 1
	v_addc_co_u32_e32 v27, vcc, 0, v23, vcc
	v_add_co_u32_e32 v28, vcc, 0x24000, v22
	s_nop 1
	v_addc_co_u32_e32 v29, vcc, 0, v23, vcc
	v_add_co_u32_e32 v40, vcc, 0x26000, v22
	s_nop 1
	v_addc_co_u32_e32 v41, vcc, 0, v23, vcc
	v_add_co_u32_e32 v42, vcc, 0x28000, v22
	s_nop 1
	v_addc_co_u32_e32 v43, vcc, 0, v23, vcc
	v_add_co_u32_e32 v94, vcc, 0x2a000, v22
	s_nop 1
	v_addc_co_u32_e32 v95, vcc, 0, v23, vcc
	v_add_co_u32_e32 v110, vcc, 0x2c000, v22
	s_nop 1
	v_addc_co_u32_e32 v111, vcc, 0, v23, vcc
	v_add_co_u32_e32 v112, vcc, 0x2e000, v22
	s_nop 1
	v_addc_co_u32_e32 v113, vcc, 0, v23, vcc
	global_load_dword v97, v[24:25], off nt
	global_load_dword v98, v[26:27], off nt
	global_load_dword v99, v[28:29], off nt
	global_load_dword v100, v[40:41], off nt
	s_nop 0
	global_load_dword v28, v[42:43], off nt
	global_load_dword v29, v[94:95], off nt
	global_load_dword v26, v[110:111], off nt
	global_load_dword v27, v[112:113], off nt
	v_add_co_u32_e32 v24, vcc, 0x30000, v22
	s_nop 1
	v_addc_co_u32_e32 v25, vcc, 0, v23, vcc
	v_add_co_u32_e32 v40, vcc, 0x32000, v22
	s_nop 1
	v_addc_co_u32_e32 v41, vcc, 0, v23, vcc
	v_add_co_u32_e32 v42, vcc, 0x34000, v22
	s_nop 1
	v_addc_co_u32_e32 v43, vcc, 0, v23, vcc
	v_add_co_u32_e32 v110, vcc, 0x36000, v22
	s_nop 1
	v_addc_co_u32_e32 v111, vcc, 0, v23, vcc
	v_add_co_u32_e32 v112, vcc, 0x38000, v22
	s_nop 1
	v_addc_co_u32_e32 v113, vcc, 0, v23, vcc
	v_add_co_u32_e32 v114, vcc, 0x3a000, v22
	s_nop 1
	v_addc_co_u32_e32 v115, vcc, 0, v23, vcc
	v_add_co_u32_e32 v116, vcc, 0x3c000, v22
	s_nop 1
	v_addc_co_u32_e32 v117, vcc, 0, v23, vcc
	v_add_co_u32_e32 v118, vcc, 0x3e000, v22
	s_nop 1
	v_addc_co_u32_e32 v119, vcc, 0, v23, vcc
	global_load_dword v93, v[24:25], off nt
	global_load_dword v94, v[40:41], off nt
	global_load_dword v95, v[42:43], off nt
	global_load_dword v96, v[110:111], off nt
	s_nop 0
	global_load_dword v24, v[112:113], off nt
	global_load_dword v25, v[114:115], off nt
	global_load_dword v22, v[116:117], off nt
	global_load_dword v23, v[118:119], off nt
	s_andn2_b64 vcc, exec, s[44:45]
	s_cbranch_vccnz .LBB0_202
; __device__ __forceinline__ void wconv_item(const float* W, int K, int Norig, int Nphys, bf16_t* WT, const float* gA, const float* gB, int split, int mapid, LAS float* scr, int item, int lane) {
;     ...
;     for (int i = 0; i < 32; ++i) { const int kk = 2 * i + (lane >> 5), k = k0 + kk;
;         float v = wv[i];
;         if (gA) v *= (k < split ? gA[k] : gB[k - split]);
;         scr[kk * 33 + (lane & 31)] = v; }
	v_lshlrev_b32_e32 v4, 2, v31
	s_movk_i32 s80, 0xf800
	s_cmpk_lt_u32 s34, 0x200
	v_lshl_add_u64 v[42:43], s[10:11], 0, v[4:5]
	s_mov_b32 s81, -1
	v_lshl_add_u64 v[40:41], s[8:9], 0, v[4:5]
	v_lshl_add_u64 v[42:43], v[42:43], 0, s[80:81]
	s_cselect_b64 vcc, -1, 0
	v_mov_b32_e32 v31, v5
	s_movk_i32 s80, 0xf808
	v_cndmask_b32_e32 v41, v43, v41, vcc
	v_cndmask_b32_e32 v40, v42, v40, vcc
	v_lshl_add_u64 v[110:111], s[10:11], 0, v[30:31]
	s_mov_b32 s81, -1
	global_load_dword v4, v[40:41], off nt
	v_lshl_add_u64 v[40:41], s[8:9], 0, v[30:31]
	v_lshl_add_u64 v[112:113], v[110:111], 0, s[80:81]
	s_movk_i32 s80, 0xf810
	v_lshl_add_u64 v[42:43], v[40:41], 0, 8
	s_mov_b32 s81, -1
	v_cndmask_b32_e32 v43, v113, v43, vcc
	v_cndmask_b32_e32 v42, v112, v42, vcc
	v_lshl_add_u64 v[112:113], v[110:111], 0, s[80:81]
	s_movk_i32 s80, 0xf818
	global_load_dword v31, v[42:43], off nt
	v_lshl_add_u64 v[42:43], v[40:41], 0, 16
	s_mov_b32 s81, -1
	v_cndmask_b32_e32 v43, v113, v43, vcc
	v_cndmask_b32_e32 v42, v112, v42, vcc
	v_lshl_add_u64 v[112:113], v[110:111], 0, s[80:81]
	s_movk_i32 s80, 0xf820
	global_load_dword v109, v[42:43], off nt
	v_lshl_add_u64 v[42:43], v[40:41], 0, 24
	s_mov_b32 s81, -1
	v_cndmask_b32_e32 v43, v113, v43, vcc
	v_cndmask_b32_e32 v42, v112, v42, vcc
	v_lshl_add_u64 v[112:113], v[110:111], 0, s[80:81]
	s_movk_i32 s80, 0xf828
	s_mov_b32 s81, -1
	global_load_dword v116, v[42:43], off nt
	v_lshl_add_u64 v[42:43], v[40:41], 0, 32
	v_lshl_add_u64 v[114:115], v[110:111], 0, s[80:81]
	s_movk_i32 s80, 0xf830
	v_cndmask_b32_e32 v43, v113, v43, vcc
	v_cndmask_b32_e32 v42, v112, v42, vcc
	v_lshl_add_u64 v[112:113], v[40:41], 0, 40
	s_mov_b32 s81, -1
	v_cndmask_b32_e32 v113, v115, v113, vcc
	v_cndmask_b32_e32 v112, v114, v112, vcc
	v_lshl_add_u64 v[114:115], v[110:111], 0, s[80:81]
	s_movk_i32 s80, 0xf838
	s_mov_b32 s81, -1
	global_load_dword v42, v[42:43], off nt
	v_lshl_add_u64 v[110:111], v[110:111], 0, s[80:81]
	global_load_dword v43, v[112:113], off nt
	v_lshl_add_u64 v[112:113], v[40:41], 0, 48
	v_lshl_add_u64 v[40:41], v[40:41], 0, 56
	v_cndmask_b32_e32 v113, v115, v113, vcc
	v_cndmask_b32_e32 v112, v114, v112, vcc
	v_cndmask_b32_e32 v41, v111, v41, vcc
	v_cndmask_b32_e32 v40, v110, v40, vcc
	global_load_dword v112, v[112:113], off nt
	s_nop 0
	global_load_dword v113, v[40:41], off nt
	v_add_u32_e32 v110, v44, v52
	s_waitcnt vmcnt(7)
	v_mul_f32_e32 v4, v106, v4
	s_waitcnt vmcnt(6)
	v_mul_f32_e32 v31, v105, v31
	s_waitcnt vmcnt(5)
	v_mul_f32_e32 v109, v107, v109
	s_waitcnt vmcnt(4)
	v_mul_f32_e32 v111, v108, v116
	ds_write_b32 v45, v4
	ds_write2_b32 v110, v31, v109 offset1:66
	ds_write_b32 v110, v111 offset:528
	s_waitcnt vmcnt(2)
	v_pk_mul_f32 v[40:41], v[38:39], v[42:43]
	s_waitcnt vmcnt(0)
	v_pk_mul_f32 v[42:43], v[36:37], v[112:113]
	s_cbranch_execnz .LBB0_57

; __device__ __forceinline__ void wconv_item(const float* W, int K, int Norig, int Nphys, bf16_t* WT, const float* gA, const float* gB, int split, int mapid, LAS float* scr, int item, int lane) {
;     ...
;     for (int i = 0; i < 32; ++i) { const int kk = 2 * i + (lane >> 5), k = k0 + kk;
;         float v = wv[i];
;         if (gA) v *= (k < split ? gA[k] : gB[k - split]);
;         scr[kk * 33 + (lane & 31)] = v; }
.LBB0_57:
	v_add_u32_e32 v4, v44, v56
	s_and_b64 vcc, exec, s[4:5]
	ds_write2_b32 v4, v40, v41 offset1:66
	ds_write2_b32 v4, v42, v43 offset0:132 offset1:198
	s_cbranch_vccnz .LBB0_203
	v_mov_b32_e32 v31, v5
	s_movk_i32 s80, 0xf840
	s_cmpk_lt_u32 s34, 0x200
	s_waitcnt vmcnt(24)
	v_lshl_add_u64 v[36:37], s[8:9], 0, v[30:31]
	v_lshl_add_u64 v[40:41], s[10:11], 0, v[30:31]
	s_mov_b32 s81, -1
	v_lshl_add_u64 v[38:39], v[36:37], 0, 64
	v_lshl_add_u64 v[42:43], v[40:41], 0, s[80:81]
	s_cselect_b64 vcc, -1, 0
	v_cndmask_b32_e32 v39, v43, v39, vcc
	v_cndmask_b32_e32 v38, v42, v38, vcc
	s_mov_b64 s[80:81], 0x48
	global_load_dword v4, v[38:39], off nt
	v_lshl_add_u64 v[38:39], v[36:37], 0, s[80:81]
	s_movk_i32 s80, 0xf848
	s_mov_b32 s81, -1
	v_lshl_add_u64 v[42:43], v[40:41], 0, s[80:81]
	v_cndmask_b32_e32 v39, v43, v39, vcc
	v_cndmask_b32_e32 v38, v42, v38, vcc
	s_mov_b64 s[80:81], 0x50
	global_load_dword v31, v[38:39], off nt
	v_lshl_add_u64 v[38:39], v[36:37], 0, s[80:81]
	s_movk_i32 s80, 0xf850
	s_mov_b32 s81, -1
	v_lshl_add_u64 v[42:43], v[40:41], 0, s[80:81]
	v_cndmask_b32_e32 v39, v43, v39, vcc
	v_cndmask_b32_e32 v38, v42, v38, vcc
	s_mov_b64 s[80:81], 0x58
	global_load_dword v105, v[38:39], off nt
	v_lshl_add_u64 v[38:39], v[36:37], 0, s[80:81]
	s_movk_i32 s80, 0xf858
	s_mov_b32 s81, -1
	v_lshl_add_u64 v[42:43], v[40:41], 0, s[80:81]
	v_cndmask_b32_e32 v39, v43, v39, vcc
	v_cndmask_b32_e32 v38, v42, v38, vcc
	s_mov_b64 s[80:81], 0x60
	global_load_dword v108, v[38:39], off nt
	v_lshl_add_u64 v[38:39], v[36:37], 0, s[80:81]
	s_movk_i32 s80, 0xf860
	s_mov_b32 s81, -1
	v_lshl_add_u64 v[42:43], v[40:41], 0, s[80:81]
	s_mov_b64 s[80:81], 0x68
	v_cndmask_b32_e32 v39, v43, v39, vcc
	v_cndmask_b32_e32 v38, v42, v38, vcc
	v_lshl_add_u64 v[42:43], v[36:37], 0, s[80:81]
	s_movk_i32 s80, 0xf868
	s_mov_b32 s81, -1
	v_lshl_add_u64 v[106:107], v[40:41], 0, s[80:81]
	v_cndmask_b32_e32 v43, v107, v43, vcc
	v_cndmask_b32_e32 v42, v106, v42, vcc
	s_mov_b64 s[80:81], 0x70
	global_load_dword v38, v[38:39], off nt
	s_waitcnt vmcnt(4)
	v_mul_f32_e32 v4, v101, v4
	global_load_dword v39, v[42:43], off nt
	v_lshl_add_u64 v[42:43], v[36:37], 0, s[80:81]
	s_movk_i32 s80, 0xf870
	s_mov_b32 s81, -1
	v_lshl_add_u64 v[106:107], v[40:41], 0, s[80:81]
	s_mov_b64 s[80:81], 0x78
	v_lshl_add_u64 v[36:37], v[36:37], 0, s[80:81]
	s_movk_i32 s80, 0xf878
	s_mov_b32 s81, -1
	v_lshl_add_u64 v[40:41], v[40:41], 0, s[80:81]
	v_cndmask_b32_e32 v43, v107, v43, vcc
	v_cndmask_b32_e32 v42, v106, v42, vcc
	v_cndmask_b32_e32 v37, v41, v37, vcc
	v_cndmask_b32_e32 v36, v40, v36, vcc
	global_load_dword v42, v[42:43], off nt
	v_add_u32_e32 v40, v44, v61
	global_load_dword v43, v[36:37], off nt
	s_waitcnt vmcnt(6)
	v_mul_f32_e32 v31, v102, v31
	s_waitcnt vmcnt(5)
	v_mul_f32_e32 v41, v103, v105
	s_waitcnt vmcnt(4)
	v_mul_f32_e32 v105, v104, v108
	ds_write2_b32 v40, v4, v31 offset1:66
	ds_write2_b32 v40, v41, v105 offset0:132 offset1:198
	s_waitcnt vmcnt(2)
	v_pk_mul_f32 v[36:37], v[34:35], v[38:39]
	s_waitcnt vmcnt(0)
	v_pk_mul_f32 v[38:39], v[32:33], v[42:43]
	s_cbranch_execnz .LBB0_60

; __device__ __forceinline__ void wconv_item(const float* W, int K, int Norig, int Nphys, bf16_t* WT, const float* gA, const float* gB, int split, int mapid, LAS float* scr, int item, int lane) {
;     ...
;     for (int i = 0; i < 32; ++i) { const int kk = 2 * i + (lane >> 5), k = k0 + kk;
;         float v = wv[i];
;         if (gA) v *= (k < split ? gA[k] : gB[k - split]);
;         scr[kk * 33 + (lane & 31)] = v; }
.LBB0_60:
	v_add_u32_e32 v4, v44, v66
	s_and_b64 vcc, exec, s[4:5]
	s_waitcnt vmcnt(24)
	ds_write2_b32 v4, v36, v37 offset1:66
	ds_write2_b32 v4, v38, v39 offset0:132 offset1:198
	s_cbranch_vccnz .LBB0_204
	v_mov_b32_e32 v31, v5
	s_waitcnt vmcnt(16)
	v_lshl_add_u64 v[32:33], s[8:9], 0, v[30:31]
	s_mov_b64 s[80:81], 0x80
	v_lshl_add_u64 v[34:35], v[32:33], 0, s[80:81]
	s_movk_i32 s80, 0xf880
	s_cmpk_lt_u32 s34, 0x200
	v_lshl_add_u64 v[36:37], s[10:11], 0, v[30:31]
	s_mov_b32 s81, -1
	v_lshl_add_u64 v[38:39], v[36:37], 0, s[80:81]
	s_cselect_b64 vcc, -1, 0
	v_cndmask_b32_e32 v35, v39, v35, vcc
	v_cndmask_b32_e32 v34, v38, v34, vcc
	s_mov_b64 s[80:81], 0x88
	global_load_dword v4, v[34:35], off nt
	v_lshl_add_u64 v[34:35], v[32:33], 0, s[80:81]
	s_movk_i32 s80, 0xf888
	s_mov_b32 s81, -1
	v_lshl_add_u64 v[38:39], v[36:37], 0, s[80:81]
	v_cndmask_b32_e32 v35, v39, v35, vcc
	v_cndmask_b32_e32 v34, v38, v34, vcc
	s_mov_b64 s[80:81], 0x90
	global_load_dword v31, v[34:35], off nt
	v_lshl_add_u64 v[34:35], v[32:33], 0, s[80:81]
	s_movk_i32 s80, 0xf890
	s_mov_b32 s81, -1
	v_lshl_add_u64 v[38:39], v[36:37], 0, s[80:81]
	v_cndmask_b32_e32 v35, v39, v35, vcc
	v_cndmask_b32_e32 v34, v38, v34, vcc
	s_mov_b64 s[80:81], 0x98
	global_load_dword v42, v[34:35], off nt
	v_lshl_add_u64 v[34:35], v[32:33], 0, s[80:81]
	s_movk_i32 s80, 0xf898
	s_mov_b32 s81, -1
	v_lshl_add_u64 v[38:39], v[36:37], 0, s[80:81]
	v_cndmask_b32_e32 v35, v39, v35, vcc
	v_cndmask_b32_e32 v34, v38, v34, vcc
	s_mov_b64 s[80:81], 0xa0
	global_load_dword v43, v[34:35], off nt
	v_lshl_add_u64 v[34:35], v[32:33], 0, s[80:81]
	s_movk_i32 s80, 0xf8a0
	s_mov_b32 s81, -1
	v_lshl_add_u64 v[38:39], v[36:37], 0, s[80:81]
	s_mov_b64 s[80:81], 0xa8
	v_cndmask_b32_e32 v35, v39, v35, vcc
	v_cndmask_b32_e32 v34, v38, v34, vcc
	v_lshl_add_u64 v[38:39], v[32:33], 0, s[80:81]
	s_movk_i32 s80, 0xf8a8
	s_mov_b32 s81, -1
	v_lshl_add_u64 v[40:41], v[36:37], 0, s[80:81]
	v_cndmask_b32_e32 v39, v41, v39, vcc
	v_cndmask_b32_e32 v38, v40, v38, vcc
	s_mov_b64 s[80:81], 0xb0
	global_load_dword v34, v[34:35], off nt
	s_waitcnt vmcnt(4)
	v_mul_f32_e32 v4, v97, v4
	global_load_dword v35, v[38:39], off nt
	v_lshl_add_u64 v[38:39], v[32:33], 0, s[80:81]
	s_movk_i32 s80, 0xf8b0
	s_mov_b32 s81, -1
	v_lshl_add_u64 v[40:41], v[36:37], 0, s[80:81]
	s_mov_b64 s[80:81], 0xb8
	v_lshl_add_u64 v[32:33], v[32:33], 0, s[80:81]
	s_movk_i32 s80, 0xf8b8
	s_mov_b32 s81, -1
	v_lshl_add_u64 v[36:37], v[36:37], 0, s[80:81]
	v_cndmask_b32_e32 v39, v41, v39, vcc
	v_cndmask_b32_e32 v38, v40, v38, vcc
	v_cndmask_b32_e32 v33, v37, v33, vcc
	v_cndmask_b32_e32 v32, v36, v32, vcc
	global_load_dword v38, v[38:39], off nt
	v_add_u32_e32 v36, v44, v71
	global_load_dword v39, v[32:33], off nt
	s_waitcnt vmcnt(6)
	v_mul_f32_e32 v31, v98, v31
	s_waitcnt vmcnt(5)
	v_mul_f32_e32 v37, v99, v42
	s_waitcnt vmcnt(4)
	v_mul_f32_e32 v40, v100, v43
	ds_write2_b32 v36, v4, v31 offset1:66
	ds_write2_b32 v36, v37, v40 offset0:132 offset1:198
	s_waitcnt vmcnt(2)
	v_pk_mul_f32 v[34:35], v[28:29], v[34:35]
	s_waitcnt vmcnt(0)
	v_pk_mul_f32 v[32:33], v[26:27], v[38:39]
	s_cbranch_execnz .LBB0_63

; __device__ __forceinline__ void wconv_item(const float* W, int K, int Norig, int Nphys, bf16_t* WT, const float* gA, const float* gB, int split, int mapid, LAS float* scr, int item, int lane) {
;     ...
;     for (int i = 0; i < 32; ++i) { const int kk = 2 * i + (lane >> 5), k = k0 + kk;
;         float v = wv[i];
;         if (gA) v *= (k < split ? gA[k] : gB[k - split]);
;         scr[kk * 33 + (lane & 31)] = v; }
.LBB0_63:
	v_add_u32_e32 v4, v44, v76
	s_and_b64 vcc, exec, s[4:5]
	s_waitcnt vmcnt(18)
	ds_write2_b32 v4, v34, v35 offset1:66
	s_waitcnt vmcnt(16)
	ds_write2_b32 v4, v32, v33 offset0:132 offset1:198
	s_cbranch_vccnz .LBB0_205
	v_mov_b32_e32 v31, v5
	s_waitcnt vmcnt(8)
	v_lshl_add_u64 v[26:27], s[8:9], 0, v[30:31]
	s_mov_b64 s[4:5], 0xc0
	v_lshl_add_u64 v[28:29], v[26:27], 0, s[4:5]
	s_movk_i32 s4, 0xf8c0
	s_cmpk_lt_u32 s34, 0x200
	v_lshl_add_u64 v[30:31], s[10:11], 0, v[30:31]
	s_mov_b32 s5, -1
	v_lshl_add_u64 v[32:33], v[30:31], 0, s[4:5]
	s_cselect_b64 vcc, -1, 0
	v_cndmask_b32_e32 v29, v33, v29, vcc
	v_cndmask_b32_e32 v28, v32, v28, vcc
	global_load_dword v4, v[28:29], off nt
	v_lshl_add_u64 v[28:29], v[26:27], 0, s[52:53]
	v_lshl_add_u64 v[32:33], v[30:31], 0, s[54:55]
	v_cndmask_b32_e32 v29, v33, v29, vcc
	v_cndmask_b32_e32 v28, v32, v28, vcc
	global_load_dword v36, v[28:29], off nt
	v_lshl_add_u64 v[28:29], v[26:27], 0, s[56:57]
	v_lshl_add_u64 v[32:33], v[30:31], 0, s[58:59]
	v_cndmask_b32_e32 v29, v33, v29, vcc
	v_cndmask_b32_e32 v28, v32, v28, vcc
	global_load_dword v37, v[28:29], off nt
	v_lshl_add_u64 v[28:29], v[26:27], 0, s[60:61]
	v_lshl_add_u64 v[32:33], v[30:31], 0, s[62:63]
	v_cndmask_b32_e32 v29, v33, v29, vcc
	v_cndmask_b32_e32 v28, v32, v28, vcc
	global_load_dword v38, v[28:29], off nt
	v_lshl_add_u64 v[28:29], v[26:27], 0, s[64:65]
	v_lshl_add_u64 v[32:33], v[30:31], 0, s[66:67]
	v_cndmask_b32_e32 v29, v33, v29, vcc
	v_cndmask_b32_e32 v28, v32, v28, vcc
	v_lshl_add_u64 v[32:33], v[26:27], 0, s[68:69]
	v_lshl_add_u64 v[34:35], v[30:31], 0, s[70:71]
	v_cndmask_b32_e32 v33, v35, v33, vcc
	v_cndmask_b32_e32 v32, v34, v32, vcc
	global_load_dword v28, v[28:29], off nt
	v_lshl_add_u64 v[34:35], v[30:31], 0, s[84:85]
	global_load_dword v29, v[32:33], off nt
	v_lshl_add_u64 v[32:33], v[26:27], 0, s[72:73]
	v_lshl_add_u64 v[26:27], v[26:27], 0, s[76:77]
	v_lshl_add_u64 v[30:31], v[30:31], 0, s[78:79]
	v_cndmask_b32_e32 v33, v35, v33, vcc
	v_cndmask_b32_e32 v32, v34, v32, vcc
	v_cndmask_b32_e32 v27, v31, v27, vcc
	v_cndmask_b32_e32 v26, v30, v26, vcc
	global_load_dword v32, v[32:33], off nt
	v_add_u32_e32 v30, v44, v80
	global_load_dword v33, v[26:27], off nt
	s_waitcnt vmcnt(7)
	v_mul_f32_e32 v4, v93, v4
	s_waitcnt vmcnt(6)
	v_mul_f32_e32 v31, v94, v36
	s_waitcnt vmcnt(5)
	v_mul_f32_e32 v34, v95, v37
	s_waitcnt vmcnt(4)
	v_mul_f32_e32 v35, v96, v38
	ds_write2_b32 v30, v4, v31 offset1:66
	ds_write2_b32 v30, v34, v35 offset0:132 offset1:198
	s_waitcnt vmcnt(2)
	v_pk_mul_f32 v[26:27], v[24:25], v[28:29]
	s_waitcnt vmcnt(0)
	v_pk_mul_f32 v[28:29], v[22:23], v[32:33]
	s_cbranch_execnz .LBB0_66

; __device__ __forceinline__ void wconv_item(const float* W, int K, int Norig, int Nphys, bf16_t* WT, const float* gA, const float* gB, int split, int mapid, LAS float* scr, int item, int lane) {
;     const int nblk = Nphys / 32, kb = item / nblk, nb = item % nblk, k0 = 64 * kb, n0 = 32 * nb;
;     const int norig = colmap(mapid, n0 + (lane & 31));
;     float wv[32];
; #pragma unroll
;     for (int i = 0; i < 32; ++i) { const int k = k0 + 2 * i + (lane >> 5); wv[i] = (norig >= 0) ? W[(size_t)k * Norig + norig] : 0.f; }
; #pragma unroll
;     for (int i = 0; i < 32; ++i) { const int kk = 2 * i + (lane >> 5), k = k0 + kk;
;         float v = wv[i];
;         if (gA) v *= (k < split ? gA[k] : gB[k - split]);
;         scr[kk * 33 + (lane & 31)] = v; }
.LBB0_73:
	s_add_i32 s4, s89, 0x2900
	s_and_b32 s34, s4, 0x1c0
	v_or_b32_e32 v38, s34, v2
	v_lshl_add_u64 v[22:23], v[4:5], 2, s[38:39]
	v_lshlrev_b32_e32 v4, 12, v38
	v_lshl_add_u64 v[22:23], v[22:23], 0, v[4:5]
	v_add_co_u32_e32 v24, vcc, 0x2000, v22
	v_cndmask_b32_e64 v39, 0, 1, s[46:47]
	s_nop 0
	v_addc_co_u32_e32 v25, vcc, 0, v23, vcc
	v_add_co_u32_e32 v26, vcc, 0x4000, v22
	v_cmp_ne_u32_e64 s[4:5], 1, v39
	s_nop 0
	v_addc_co_u32_e32 v27, vcc, 0, v23, vcc
	v_add_co_u32_e32 v28, vcc, 0x6000, v22
	v_add_lshl_u32 v102, s34, v2, 2
	s_nop 0
	v_addc_co_u32_e32 v29, vcc, 0, v23, vcc
	v_add_co_u32_e32 v30, vcc, 0x8000, v22
	s_nop 1
	v_addc_co_u32_e32 v31, vcc, 0, v23, vcc
	v_add_co_u32_e32 v32, vcc, 0xa000, v22
	s_nop 1
	v_addc_co_u32_e32 v33, vcc, 0, v23, vcc
	v_add_co_u32_e32 v34, vcc, 0xc000, v22
	s_nop 1
	v_addc_co_u32_e32 v35, vcc, 0, v23, vcc
	v_add_co_u32_e32 v40, vcc, 0xe000, v22
	s_nop 1
	v_addc_co_u32_e32 v41, vcc, 0, v23, vcc
	global_load_dword v104, v[22:23], off nt
	global_load_dword v103, v[24:25], off nt
	global_load_dword v105, v[26:27], off nt
	global_load_dword v106, v[28:29], off nt
	global_load_dword v36, v[30:31], off nt
	global_load_dword v37, v[32:33], off nt
	s_nop 0
	global_load_dword v34, v[34:35], off nt
	s_nop 0
	global_load_dword v35, v[40:41], off nt
	v_add_co_u32_e32 v24, vcc, 0x10000, v22
	s_nop 1
	v_addc_co_u32_e32 v25, vcc, 0, v23, vcc
	v_add_co_u32_e32 v26, vcc, 0x12000, v22
	s_nop 1
	v_addc_co_u32_e32 v27, vcc, 0, v23, vcc
	v_add_co_u32_e32 v28, vcc, 0x14000, v22
	s_nop 1
	v_addc_co_u32_e32 v29, vcc, 0, v23, vcc
	v_add_co_u32_e32 v30, vcc, 0x16000, v22
	s_nop 1
	v_addc_co_u32_e32 v31, vcc, 0, v23, vcc
	v_add_co_u32_e32 v32, vcc, 0x18000, v22
	s_nop 1
	v_addc_co_u32_e32 v33, vcc, 0, v23, vcc
	v_add_co_u32_e32 v40, vcc, 0x1a000, v22
	s_nop 1
	v_addc_co_u32_e32 v41, vcc, 0, v23, vcc
	v_add_co_u32_e32 v42, vcc, 0x1c000, v22
	s_nop 1
	v_addc_co_u32_e32 v43, vcc, 0, v23, vcc
	v_add_co_u32_e32 v94, vcc, 0x1e000, v22
	s_nop 1
	v_addc_co_u32_e32 v95, vcc, 0, v23, vcc
	global_load_dword v98, v[24:25], off nt
	global_load_dword v99, v[26:27], off nt
	global_load_dword v100, v[28:29], off nt
	global_load_dword v101, v[30:31], off nt
	s_nop 0
	global_load_dword v32, v[32:33], off nt
	s_nop 0
	global_load_dword v33, v[40:41], off nt
	global_load_dword v30, v[42:43], off nt
	global_load_dword v31, v[94:95], off nt
	v_add_co_u32_e32 v24, vcc, 0x20000, v22
	s_nop 1
	v_addc_co_u32_e32 v25, vcc, 0, v23, vcc
	v_add_co_u32_e32 v26, vcc, 0x22000, v22
	s_nop 1
	v_addc_co_u32_e32 v27, vcc, 0, v23, vcc
	v_add_co_u32_e32 v28, vcc, 0x24000, v22
	s_nop 1
	v_addc_co_u32_e32 v29, vcc, 0, v23, vcc
	v_add_co_u32_e32 v40, vcc, 0x26000, v22
	s_nop 1
	v_addc_co_u32_e32 v41, vcc, 0, v23, vcc
	v_add_co_u32_e32 v42, vcc, 0x28000, v22
	s_nop 1
	v_addc_co_u32_e32 v43, vcc, 0, v23, vcc
	v_add_co_u32_e32 v108, vcc, 0x2a000, v22
	s_nop 1
	v_addc_co_u32_e32 v109, vcc, 0, v23, vcc
	v_add_co_u32_e32 v110, vcc, 0x2c000, v22
	s_nop 1
	v_addc_co_u32_e32 v111, vcc, 0, v23, vcc
	v_add_co_u32_e32 v112, vcc, 0x2e000, v22
	s_nop 1
	v_addc_co_u32_e32 v113, vcc, 0, v23, vcc
	global_load_dword v94, v[24:25], off nt
	global_load_dword v95, v[26:27], off nt
	global_load_dword v96, v[28:29], off nt
	global_load_dword v97, v[40:41], off nt
	s_nop 0
	global_load_dword v28, v[42:43], off nt
	global_load_dword v29, v[108:109], off nt
	global_load_dword v26, v[110:111], off nt
	global_load_dword v27, v[112:113], off nt
	v_add_co_u32_e32 v24, vcc, 0x30000, v22
	s_nop 1
	v_addc_co_u32_e32 v25, vcc, 0, v23, vcc
	v_add_co_u32_e32 v40, vcc, 0x32000, v22
	s_nop 1
	v_addc_co_u32_e32 v41, vcc, 0, v23, vcc
	v_add_co_u32_e32 v108, vcc, 0x34000, v22
	s_nop 1
	v_addc_co_u32_e32 v109, vcc, 0, v23, vcc
	v_add_co_u32_e32 v110, vcc, 0x36000, v22
	s_nop 1
	v_addc_co_u32_e32 v111, vcc, 0, v23, vcc
	v_add_co_u32_e32 v112, vcc, 0x38000, v22
	s_nop 1
	v_addc_co_u32_e32 v113, vcc, 0, v23, vcc
	v_add_co_u32_e32 v114, vcc, 0x3a000, v22
	s_nop 1
	v_addc_co_u32_e32 v115, vcc, 0, v23, vcc
	v_add_co_u32_e32 v116, vcc, 0x3c000, v22
	s_nop 1
	v_addc_co_u32_e32 v117, vcc, 0, v23, vcc
	v_add_co_u32_e32 v118, vcc, 0x3e000, v22
	s_nop 1
	v_addc_co_u32_e32 v119, vcc, 0, v23, vcc
	global_load_dword v4, v[24:25], off nt
	global_load_dword v42, v[40:41], off nt
	global_load_dword v43, v[108:109], off nt
	global_load_dword v93, v[110:111], off nt
	s_nop 0
	global_load_dword v24, v[112:113], off nt
	global_load_dword v25, v[114:115], off nt
	global_load_dword v22, v[116:117], off nt
	global_load_dword v23, v[118:119], off nt
	s_andn2_b64 vcc, exec, s[46:47]
	s_cbranch_vccnz .LBB0_198
	v_lshlrev_b32_e32 v107, 2, v38
	global_load_dword v108, v102, s[36:37] offset:8
	global_load_dword v109, v102, s[36:37] offset:16
	global_load_dword v110, v102, s[36:37] offset:24
	global_load_dword v38, v102, s[36:37] offset:32
	global_load_dword v39, v102, s[36:37] offset:40
	global_load_dword v40, v102, s[36:37] offset:48
	global_load_dword v41, v102, s[36:37] offset:56
	s_nop 0
	global_load_dword v107, v107, s[36:37]
	v_add_u32_e32 v111, v44, v52
	s_waitcnt vmcnt(7)
	v_mul_f32_e32 v108, v103, v108
	s_waitcnt vmcnt(6)
	v_mul_f32_e32 v109, v105, v109
	s_waitcnt vmcnt(5)
	v_mul_f32_e32 v110, v106, v110
	s_waitcnt vmcnt(3)
	v_pk_mul_f32 v[38:39], v[36:37], v[38:39]
	s_waitcnt vmcnt(1)
	v_pk_mul_f32 v[40:41], v[34:35], v[40:41]
	s_waitcnt vmcnt(0)
	v_mul_f32_e32 v107, v104, v107
	ds_write_b32 v45, v107
	ds_write2_b32 v111, v108, v109 offset1:66
	ds_write_b32 v111, v110 offset:528
	s_cbranch_execnz .LBB0_76

; __device__ __forceinline__ void wconv_item(const float* W, int K, int Norig, int Nphys, bf16_t* WT, const float* gA, const float* gB, int split, int mapid, LAS float* scr, int item, int lane) {
;     const int nblk = Nphys / 32, kb = item / nblk, nb = item % nblk, k0 = 64 * kb, n0 = 32 * nb;
;     const int norig = colmap(mapid, n0 + (lane & 31));
;     float wv[32];
; #pragma unroll
;     for (int i = 0; i < 32; ++i) { const int k = k0 + 2 * i + (lane >> 5); wv[i] = (norig >= 0) ? W[(size_t)k * Norig + norig] : 0.f; }
; #pragma unroll
;     for (int i = 0; i < 32; ++i) { const int kk = 2 * i + (lane >> 5), k = k0 + kk;
;         float v = wv[i];
;         if (gA) v *= (k < split ? gA[k] : gB[k - split]);
;         scr[kk * 33 + (lane & 31)] = v; }
.LBB0_92:
	s_and_b32 s4, 0xffff, s80
	s_lshl_b32 s82, s4, 6
	v_or_b32_e32 v38, s82, v2
	v_lshl_add_u64 v[22:23], v[4:5], 2, s[30:31]
	v_mul_u32_u24_e32 v4, 0x300, v38
	v_lshlrev_b32_e32 v4, 2, v4
	v_lshl_add_u64 v[22:23], v[22:23], 0, v[4:5]
	v_add_co_u32_e32 v24, vcc, 0x1000, v22
	s_movk_i32 s4, 0x4000
	s_nop 0
	v_addc_co_u32_e32 v25, vcc, 0, v23, vcc
	v_add_co_u32_e32 v26, vcc, 0x3000, v22
	v_cndmask_b32_e64 v39, 0, 1, s[48:49]
	s_nop 0
	v_addc_co_u32_e32 v27, vcc, 0, v23, vcc
	v_add_co_u32_e32 v28, vcc, s4, v22
	s_movk_i32 s4, 0x6000
	s_nop 0
	v_addc_co_u32_e32 v29, vcc, 0, v23, vcc
	v_add_co_u32_e32 v30, vcc, s4, v22
	s_mov_b32 s4, 0xa000
	s_nop 0
	v_addc_co_u32_e32 v31, vcc, 0, v23, vcc
	v_add_co_u32_e32 v32, vcc, 0x7000, v22
	s_nop 1
	v_addc_co_u32_e32 v33, vcc, 0, v23, vcc
	v_add_co_u32_e32 v34, vcc, 0x9000, v22
	s_nop 1
	v_addc_co_u32_e32 v35, vcc, 0, v23, vcc
	v_add_co_u32_e32 v40, vcc, s4, v22
	s_mov_b32 s4, 0xc000
	s_nop 0
	v_addc_co_u32_e32 v41, vcc, 0, v23, vcc
	global_load_dword v103, v[22:23], off nt
	global_load_dword v102, v[24:25], off offset:2048 nt
	global_load_dword v104, v[26:27], off nt
	global_load_dword v105, v[28:29], off offset:2048 nt
	global_load_dword v36, v[30:31], off nt
	global_load_dword v37, v[32:33], off offset:2048 nt
	s_nop 0
	global_load_dword v34, v[34:35], off nt
	s_nop 0
	global_load_dword v35, v[40:41], off offset:2048 nt
	v_add_co_u32_e32 v24, vcc, s4, v22
	s_mov_b32 s4, 0x10000
	s_nop 0
	v_addc_co_u32_e32 v25, vcc, 0, v23, vcc
	v_add_co_u32_e32 v26, vcc, 0xd000, v22
	s_nop 1
	v_addc_co_u32_e32 v27, vcc, 0, v23, vcc
	v_add_co_u32_e32 v28, vcc, 0xf000, v22
	s_nop 1
	v_addc_co_u32_e32 v29, vcc, 0, v23, vcc
	v_add_co_u32_e32 v30, vcc, s4, v22
	s_mov_b32 s4, 0x12000
	s_nop 0
	v_addc_co_u32_e32 v31, vcc, 0, v23, vcc
	v_add_co_u32_e32 v32, vcc, s4, v22
	s_mov_b32 s4, 0x16000
	s_nop 0
	v_addc_co_u32_e32 v33, vcc, 0, v23, vcc
	v_add_co_u32_e32 v40, vcc, 0x13000, v22
	s_nop 1
	v_addc_co_u32_e32 v41, vcc, 0, v23, vcc
	v_add_co_u32_e32 v42, vcc, 0x15000, v22
	s_nop 1
	v_addc_co_u32_e32 v43, vcc, 0, v23, vcc
	v_add_co_u32_e32 v94, vcc, s4, v22
	s_mov_b32 s4, 0x18000
	s_nop 0
	v_addc_co_u32_e32 v95, vcc, 0, v23, vcc
	global_load_dword v98, v[24:25], off nt
	global_load_dword v99, v[26:27], off offset:2048 nt
	global_load_dword v100, v[28:29], off nt
	global_load_dword v101, v[30:31], off offset:2048 nt
	s_nop 0
	global_load_dword v32, v[32:33], off nt
	s_nop 0
	global_load_dword v33, v[40:41], off offset:2048 nt
	global_load_dword v30, v[42:43], off nt
	global_load_dword v31, v[94:95], off offset:2048 nt
	v_add_co_u32_e32 v24, vcc, s4, v22
	s_mov_b32 s4, 0x1c000
	s_nop 0
	v_addc_co_u32_e32 v25, vcc, 0, v23, vcc
	v_add_co_u32_e32 v26, vcc, 0x19000, v22
	s_nop 1
	v_addc_co_u32_e32 v27, vcc, 0, v23, vcc
	v_add_co_u32_e32 v28, vcc, 0x1b000, v22
	s_nop 1
	v_addc_co_u32_e32 v29, vcc, 0, v23, vcc
	v_add_co_u32_e32 v40, vcc, s4, v22
	s_mov_b32 s4, 0x1e000
	s_nop 0
	v_addc_co_u32_e32 v41, vcc, 0, v23, vcc
	v_add_co_u32_e32 v42, vcc, s4, v22
	s_mov_b32 s4, 0x22000
	s_nop 0
	v_addc_co_u32_e32 v43, vcc, 0, v23, vcc
	v_add_co_u32_e32 v106, vcc, 0x1f000, v22
	s_nop 1
	v_addc_co_u32_e32 v107, vcc, 0, v23, vcc
	v_add_co_u32_e32 v108, vcc, 0x21000, v22
	s_nop 1
	v_addc_co_u32_e32 v109, vcc, 0, v23, vcc
	v_add_co_u32_e32 v110, vcc, s4, v22
	s_mov_b32 s4, 0x24000
	s_nop 0
	v_addc_co_u32_e32 v111, vcc, 0, v23, vcc
	global_load_dword v94, v[24:25], off nt
	global_load_dword v95, v[26:27], off offset:2048 nt
	global_load_dword v96, v[28:29], off nt
	global_load_dword v97, v[40:41], off offset:2048 nt
	s_nop 0
	global_load_dword v28, v[42:43], off nt
	global_load_dword v29, v[106:107], off offset:2048 nt
	global_load_dword v26, v[108:109], off nt
	global_load_dword v27, v[110:111], off offset:2048 nt
	v_add_co_u32_e32 v24, vcc, s4, v22
	s_mov_b32 s4, 0x28000
	s_nop 0
	v_addc_co_u32_e32 v25, vcc, 0, v23, vcc
	v_add_co_u32_e32 v40, vcc, 0x25000, v22
	s_nop 1
	v_addc_co_u32_e32 v41, vcc, 0, v23, vcc
	v_add_co_u32_e32 v106, vcc, 0x27000, v22
	s_nop 1
	v_addc_co_u32_e32 v107, vcc, 0, v23, vcc
	v_add_co_u32_e32 v108, vcc, s4, v22
	s_mov_b32 s4, 0x2a000
	s_nop 0
	v_addc_co_u32_e32 v109, vcc, 0, v23, vcc
	v_add_co_u32_e32 v110, vcc, s4, v22
	v_cmp_ne_u32_e64 s[4:5], 1, v39
	s_nop 0
	v_addc_co_u32_e32 v111, vcc, 0, v23, vcc
	v_add_co_u32_e32 v112, vcc, 0x2b000, v22
	s_nop 1
	v_addc_co_u32_e32 v113, vcc, 0, v23, vcc
	v_add_co_u32_e32 v114, vcc, 0x2d000, v22
	s_nop 1
	v_addc_co_u32_e32 v115, vcc, 0, v23, vcc
	v_add_co_u32_e32 v116, vcc, 0x2e000, v22
	s_nop 1
	v_addc_co_u32_e32 v117, vcc, 0, v23, vcc
	global_load_dword v4, v[24:25], off nt
	global_load_dword v42, v[40:41], off offset:2048 nt
	global_load_dword v43, v[106:107], off nt
	global_load_dword v93, v[108:109], off offset:2048 nt
	s_nop 0
	global_load_dword v24, v[110:111], off nt
	global_load_dword v25, v[112:113], off offset:2048 nt
	global_load_dword v22, v[114:115], off nt
	global_load_dword v23, v[116:117], off offset:2048 nt
	s_andn2_b64 vcc, exec, s[48:49]
	v_add_lshl_u32 v106, s82, v2, 2
	s_cbranch_vccnz .LBB0_194
	v_lshlrev_b32_e32 v107, 2, v38
	global_load_dword v108, v106, s[28:29] offset:8
	global_load_dword v109, v106, s[28:29] offset:16
	global_load_dword v110, v106, s[28:29] offset:24
	global_load_dword v38, v106, s[28:29] offset:32
	global_load_dword v39, v106, s[28:29] offset:40
	global_load_dword v40, v106, s[28:29] offset:48
	global_load_dword v41, v106, s[28:29] offset:56
	s_nop 0
	global_load_dword v107, v107, s[28:29]
	v_add_u32_e32 v111, v44, v52
	s_waitcnt vmcnt(7)
	v_mul_f32_e32 v108, v102, v108
	s_waitcnt vmcnt(6)
	v_mul_f32_e32 v109, v104, v109
	s_waitcnt vmcnt(5)
	v_mul_f32_e32 v110, v105, v110
	s_waitcnt vmcnt(3)
	v_pk_mul_f32 v[38:39], v[36:37], v[38:39]
	s_waitcnt vmcnt(1)
	v_pk_mul_f32 v[40:41], v[34:35], v[40:41]
	s_waitcnt vmcnt(0)
	v_mul_f32_e32 v107, v103, v107
	ds_write_b32 v45, v107
	ds_write2_b32 v111, v108, v109 offset1:66
	ds_write_b32 v111, v110 offset:528
	s_cbranch_execnz .LBB0_95

; __device__ __forceinline__ void wconv_item(const float* W, int K, int Norig, int Nphys, bf16_t* WT, const float* gA, const float* gB, int split, int mapid, LAS float* scr, int item, int lane) {
;     ...
;     const int norig = colmap(mapid, n0 + (lane & 31));
;     float wv[32];
; #pragma unroll
;     for (int i = 0; i < 32; ++i) { const int k = k0 + 2 * i + (lane >> 5); wv[i] = (norig >= 0) ? W[(size_t)k * Norig + norig] : 0.f; }
.LBB0_114:
	s_or_b64 exec, exec, s[4:5]
	s_lshl_b32 s80, s82, 6
	v_cmp_lt_i32_e32 vcc, -1, v4
	v_or_b32_e32 v38, s80, v2
	v_lshl_add_u64 v[40:41], v[4:5], 2, s[26:27]
	v_mov_b32_e32 v102, 0
	v_mov_b32_e32 v103, 0
	s_and_saveexec_b64 s[4:5], vcc
	s_cbranch_execz .LBB0_116
	v_mad_i64_i32 v[22:23], s[82:83], v38, s92, v[40:41]
	global_load_dword v103, v[22:23], off nt
.LBB0_116:
	s_or_b64 exec, exec, s[4:5]
	s_and_saveexec_b64 s[4:5], vcc
	s_cbranch_execz .LBB0_118
	v_or_b32_e32 v4, 2, v38
	v_mad_i64_i32 v[22:23], s[82:83], v4, s92, v[40:41]
	global_load_dword v102, v[22:23], off nt
.LBB0_118:
	s_or_b64 exec, exec, s[4:5]
	v_mov_b32_e32 v104, 0
	v_mov_b32_e32 v105, 0
	s_and_saveexec_b64 s[4:5], vcc
	s_cbranch_execz .LBB0_120
	v_or_b32_e32 v4, 4, v38
	v_mad_i64_i32 v[22:23], s[82:83], v4, s92, v[40:41]
	global_load_dword v105, v[22:23], off nt
.LBB0_120:
	s_or_b64 exec, exec, s[4:5]
	s_and_saveexec_b64 s[4:5], vcc
	s_cbranch_execz .LBB0_122
	v_or_b32_e32 v4, 6, v38
	v_mad_i64_i32 v[22:23], s[82:83], v4, s92, v[40:41]
	global_load_dword v104, v[22:23], off nt
.LBB0_122:
	s_or_b64 exec, exec, s[4:5]
	v_mov_b32_e32 v35, 0
	v_mov_b32_e32 v34, 0
	s_and_saveexec_b64 s[4:5], vcc
	s_cbranch_execz .LBB0_124
	v_or_b32_e32 v4, 8, v38
	v_mad_i64_i32 v[22:23], s[82:83], v4, s92, v[40:41]
	global_load_dword v34, v[22:23], off nt
.LBB0_124:
	s_or_b64 exec, exec, s[4:5]
	s_and_saveexec_b64 s[4:5], vcc
	s_cbranch_execz .LBB0_126
	v_or_b32_e32 v4, 10, v38
	v_mad_i64_i32 v[22:23], s[82:83], v4, s92, v[40:41]
	global_load_dword v35, v[22:23], off nt
.LBB0_126:
	s_or_b64 exec, exec, s[4:5]
	v_mov_b32_e32 v37, 0
	v_mov_b32_e32 v36, 0
	s_and_saveexec_b64 s[4:5], vcc
	s_cbranch_execz .LBB0_128
	v_or_b32_e32 v4, 12, v38
	v_mad_i64_i32 v[22:23], s[82:83], v4, s92, v[40:41]
	global_load_dword v36, v[22:23], off nt
.LBB0_128:
	s_or_b64 exec, exec, s[4:5]
	s_and_saveexec_b64 s[4:5], vcc
	s_cbranch_execz .LBB0_130
	v_or_b32_e32 v4, 14, v38
	v_mad_i64_i32 v[22:23], s[82:83], v4, s92, v[40:41]
	global_load_dword v37, v[22:23], off nt
.LBB0_130:
	s_or_b64 exec, exec, s[4:5]
	v_mov_b32_e32 v98, 0
	v_mov_b32_e32 v99, 0
	s_and_saveexec_b64 s[4:5], vcc
	s_cbranch_execz .LBB0_132
	v_or_b32_e32 v4, 16, v38
	v_mad_i64_i32 v[22:23], s[82:83], v4, s92, v[40:41]
	global_load_dword v99, v[22:23], off nt
.LBB0_132:
	s_or_b64 exec, exec, s[4:5]
	s_and_saveexec_b64 s[4:5], vcc
	s_cbranch_execz .LBB0_134
	v_or_b32_e32 v4, 18, v38
	v_mad_i64_i32 v[22:23], s[82:83], v4, s92, v[40:41]
	global_load_dword v98, v[22:23], off nt
.LBB0_134:
	s_or_b64 exec, exec, s[4:5]
	v_mov_b32_e32 v100, 0
	v_mov_b32_e32 v101, 0
	s_and_saveexec_b64 s[4:5], vcc
	s_cbranch_execz .LBB0_136
	v_or_b32_e32 v4, 20, v38
	v_mad_i64_i32 v[22:23], s[82:83], v4, s92, v[40:41]
	global_load_dword v101, v[22:23], off nt
.LBB0_136:
	s_or_b64 exec, exec, s[4:5]
	s_and_saveexec_b64 s[4:5], vcc
	s_cbranch_execz .LBB0_138
	v_or_b32_e32 v4, 22, v38
	v_mad_i64_i32 v[22:23], s[82:83], v4, s92, v[40:41]
	global_load_dword v100, v[22:23], off nt
.LBB0_138:
	s_or_b64 exec, exec, s[4:5]
	v_mov_b32_e32 v31, 0
	v_mov_b32_e32 v30, 0
	s_and_saveexec_b64 s[4:5], vcc
	s_cbranch_execz .LBB0_140
	v_or_b32_e32 v4, 24, v38
	v_mad_i64_i32 v[22:23], s[82:83], v4, s92, v[40:41]
	global_load_dword v30, v[22:23], off nt
.LBB0_140:
	s_or_b64 exec, exec, s[4:5]
	s_and_saveexec_b64 s[4:5], vcc
	s_cbranch_execz .LBB0_142
	v_or_b32_e32 v4, 26, v38
	v_mad_i64_i32 v[22:23], s[82:83], v4, s92, v[40:41]
	global_load_dword v31, v[22:23], off nt
.LBB0_142:
	s_or_b64 exec, exec, s[4:5]
	v_mov_b32_e32 v33, 0
	v_mov_b32_e32 v32, 0
	s_and_saveexec_b64 s[4:5], vcc
	s_cbranch_execz .LBB0_144
	v_or_b32_e32 v4, 28, v38
	v_mad_i64_i32 v[22:23], s[82:83], v4, s92, v[40:41]
	global_load_dword v32, v[22:23], off nt
.LBB0_144:
	s_or_b64 exec, exec, s[4:5]
	s_and_saveexec_b64 s[4:5], vcc
	s_cbranch_execz .LBB0_146
	v_or_b32_e32 v4, 30, v38
	v_mad_i64_i32 v[22:23], s[82:83], v4, s92, v[40:41]
	global_load_dword v33, v[22:23], off nt
.LBB0_146:
	s_or_b64 exec, exec, s[4:5]
	v_mov_b32_e32 v94, 0
	v_mov_b32_e32 v95, 0
	s_and_saveexec_b64 s[4:5], vcc
	s_cbranch_execz .LBB0_148
	v_or_b32_e32 v4, 32, v38
	v_mad_i64_i32 v[22:23], s[82:83], v4, s92, v[40:41]
	global_load_dword v95, v[22:23], off nt
.LBB0_148:
	s_or_b64 exec, exec, s[4:5]
	s_and_saveexec_b64 s[4:5], vcc
	s_cbranch_execz .LBB0_150
	v_or_b32_e32 v4, 34, v38
	v_mad_i64_i32 v[22:23], s[82:83], v4, s92, v[40:41]
	global_load_dword v94, v[22:23], off nt
.LBB0_150:
	s_or_b64 exec, exec, s[4:5]
	v_mov_b32_e32 v96, 0
	v_mov_b32_e32 v97, 0
	s_and_saveexec_b64 s[4:5], vcc
	s_cbranch_execz .LBB0_152
	v_or_b32_e32 v4, 36, v38
	v_mad_i64_i32 v[22:23], s[82:83], v4, s92, v[40:41]
	global_load_dword v97, v[22:23], off nt
.LBB0_152:
	s_or_b64 exec, exec, s[4:5]
	s_and_saveexec_b64 s[4:5], vcc
	s_cbranch_execz .LBB0_154
	v_or_b32_e32 v4, 38, v38
	v_mad_i64_i32 v[22:23], s[82:83], v4, s92, v[40:41]
	global_load_dword v96, v[22:23], off nt
.LBB0_154:
	s_or_b64 exec, exec, s[4:5]
	v_mov_b32_e32 v27, 0
	v_mov_b32_e32 v26, 0
	s_and_saveexec_b64 s[4:5], vcc
	s_cbranch_execz .LBB0_156
	v_or_b32_e32 v4, 40, v38
	v_mad_i64_i32 v[22:23], s[82:83], v4, s92, v[40:41]
	global_load_dword v26, v[22:23], off nt
; __device__ __forceinline__ void wconv_item(const float* W, int K, int Norig, int Nphys, bf16_t* WT, const float* gA, const float* gB, int split, int mapid, LAS float* scr, int item, int lane) {
;     ...
;     for (int i = 0; i < 32; ++i) { const int k = k0 + 2 * i + (lane >> 5); wv[i] = (norig >= 0) ? W[(size_t)k * Norig + norig] : 0.f; }
; #pragma unroll
;     for (int i = 0; i < 32; ++i) { const int kk = 2 * i + (lane >> 5), k = k0 + kk;
;         float v = wv[i];
;         if (gA) v *= (k < split ? gA[k] : gB[k - split]);
;         scr[kk * 33 + (lane & 31)] = v; }
.LBB0_156:
	s_or_b64 exec, exec, s[4:5]
	s_and_saveexec_b64 s[4:5], vcc
	s_cbranch_execz .LBB0_158
	v_or_b32_e32 v4, 42, v38
	v_mad_i64_i32 v[22:23], s[82:83], v4, s92, v[40:41]
	global_load_dword v27, v[22:23], off nt
.LBB0_158:
	s_or_b64 exec, exec, s[4:5]
	v_mov_b32_e32 v29, 0
	v_mov_b32_e32 v28, 0
	s_and_saveexec_b64 s[4:5], vcc
	s_cbranch_execz .LBB0_160
	v_or_b32_e32 v4, 44, v38
	v_mad_i64_i32 v[22:23], s[82:83], v4, s92, v[40:41]
	global_load_dword v28, v[22:23], off nt
.LBB0_160:
	s_or_b64 exec, exec, s[4:5]
	s_and_saveexec_b64 s[4:5], vcc
	s_cbranch_execz .LBB0_162
	v_or_b32_e32 v4, 46, v38
	v_mad_i64_i32 v[22:23], s[82:83], v4, s92, v[40:41]
	global_load_dword v29, v[22:23], off nt
.LBB0_162:
	s_or_b64 exec, exec, s[4:5]
	v_mov_b32_e32 v4, 0
	v_mov_b32_e32 v42, 0
	s_and_saveexec_b64 s[4:5], vcc
	s_cbranch_execz .LBB0_164
	v_or_b32_e32 v22, 48, v38
	v_mad_i64_i32 v[22:23], s[82:83], v22, s92, v[40:41]
	global_load_dword v42, v[22:23], off nt
.LBB0_164:
	s_or_b64 exec, exec, s[4:5]
	s_and_saveexec_b64 s[4:5], vcc
	s_cbranch_execz .LBB0_166
	v_or_b32_e32 v4, 50, v38
	v_mad_i64_i32 v[22:23], s[82:83], v4, s92, v[40:41]
	global_load_dword v4, v[22:23], off nt
.LBB0_166:
	s_or_b64 exec, exec, s[4:5]
	v_mov_b32_e32 v43, 0
	v_mov_b32_e32 v93, 0
	s_and_saveexec_b64 s[4:5], vcc
	s_cbranch_execz .LBB0_168
	v_or_b32_e32 v22, 52, v38
	v_mad_i64_i32 v[22:23], s[82:83], v22, s92, v[40:41]
	global_load_dword v93, v[22:23], off nt
.LBB0_168:
	s_or_b64 exec, exec, s[4:5]
	s_and_saveexec_b64 s[4:5], vcc
	s_cbranch_execz .LBB0_170
	v_or_b32_e32 v22, 54, v38
	v_mad_i64_i32 v[22:23], s[82:83], v22, s92, v[40:41]
	global_load_dword v43, v[22:23], off nt
.LBB0_170:
	s_or_b64 exec, exec, s[4:5]
	v_mov_b32_e32 v23, 0
	v_mov_b32_e32 v22, 0
	s_and_saveexec_b64 s[4:5], vcc
	s_cbranch_execz .LBB0_172
	v_or_b32_e32 v22, 56, v38
	v_mad_i64_i32 v[24:25], s[82:83], v22, s92, v[40:41]
	global_load_dword v22, v[24:25], off nt
.LBB0_172:
	s_or_b64 exec, exec, s[4:5]
	s_and_saveexec_b64 s[4:5], vcc
	s_cbranch_execz .LBB0_174
	v_or_b32_e32 v23, 58, v38
	v_mad_i64_i32 v[24:25], s[82:83], v23, s92, v[40:41]
	global_load_dword v23, v[24:25], off nt
.LBB0_174:
	s_or_b64 exec, exec, s[4:5]
	v_mov_b32_e32 v25, 0
	v_mov_b32_e32 v24, 0
	s_and_saveexec_b64 s[4:5], vcc
	s_cbranch_execz .LBB0_176
	v_or_b32_e32 v24, 60, v38
	v_mad_i64_i32 v[106:107], s[82:83], v24, s92, v[40:41]
	global_load_dword v24, v[106:107], off nt
.LBB0_176:
	s_or_b64 exec, exec, s[4:5]
	s_and_saveexec_b64 s[4:5], vcc
	s_cbranch_execz .LBB0_178
	v_or_b32_e32 v25, 62, v38
	v_mad_i64_i32 v[40:41], s[82:83], v25, s92, v[40:41]
	global_load_dword v25, v[40:41], off nt
.LBB0_178:
	s_or_b64 exec, exec, s[4:5]
	v_cndmask_b32_e64 v39, 0, 1, s[50:51]
	v_cmp_ne_u32_e64 s[4:5], 1, v39
	s_andn2_b64 vcc, exec, s[50:51]
	v_add_u32_e32 v106, v44, v52
	s_cbranch_vccnz .LBB0_189
	v_ashrrev_i32_e32 v39, 31, v38
	v_cmp_gt_i32_e32 vcc, s91, v38
	v_or_b32_e32 v107, s80, v51
	v_lshl_add_u64 v[40:41], v[38:39], 2, s[24:25]
	v_cndmask_b32_e64 v39, -1, 0, vcc
	v_cndmask_b32_e64 v38, v92, 0, vcc
	v_cmp_gt_i32_e32 vcc, s91, v107
	v_or_b32_e32 v107, s80, v53
	s_ashr_i32 s81, s80, 31
	v_cndmask_b32_e64 v109, -1, 0, vcc
	v_cndmask_b32_e64 v108, v92, 0, vcc
	v_cmp_gt_i32_e32 vcc, s91, v107
	v_or_b32_e32 v107, s80, v54
	v_lshl_add_u64 v[38:39], v[40:41], 0, v[38:39]
	v_cndmask_b32_e64 v111, -1, 0, vcc
	v_cndmask_b32_e64 v110, v92, 0, vcc
	v_cmp_gt_i32_e32 vcc, s91, v107
	v_or_b32_e32 v107, s80, v55
	v_lshl_add_u64 v[40:41], s[80:81], 0, v[2:3]
	v_cndmask_b32_e64 v113, -1, 0, vcc
	v_cndmask_b32_e64 v112, v92, 0, vcc
	v_cmp_gt_i32_e32 vcc, s91, v107
	v_or_b32_e32 v107, s80, v57
	v_lshl_add_u64 v[40:41], v[40:41], 2, s[24:25]
	v_cndmask_b32_e64 v115, -1, 0, vcc
	v_cndmask_b32_e64 v114, v92, 0, vcc
	v_cmp_gt_i32_e32 vcc, s91, v107
	v_or_b32_e32 v107, s80, v58
	v_lshl_add_u64 v[108:109], v[40:41], 0, v[108:109]
	v_cndmask_b32_e64 v117, -1, 0, vcc
	v_cndmask_b32_e64 v116, v92, 0, vcc
	v_cmp_gt_i32_e32 vcc, s91, v107
	v_or_b32_e32 v107, s80, v59
	v_lshl_add_u64 v[110:111], v[40:41], 0, v[110:111]
	v_cndmask_b32_e64 v119, -1, 0, vcc
	v_cndmask_b32_e64 v118, v92, 0, vcc
	v_cmp_gt_i32_e32 vcc, s91, v107
	v_lshl_add_u64 v[112:113], v[40:41], 0, v[112:113]
	v_lshl_add_u64 v[114:115], v[40:41], 0, v[114:115]
	v_cndmask_b32_e64 v121, -1, 0, vcc
	v_cndmask_b32_e64 v120, v92, 0, vcc
	v_lshl_add_u64 v[116:117], v[40:41], 0, v[116:117]
	v_lshl_add_u64 v[118:119], v[40:41], 0, v[118:119]
	v_lshl_add_u64 v[40:41], v[40:41], 0, v[120:121]
	global_load_dword v107, v[38:39], off nt
	global_load_dword v120, v[108:109], off offset:8 nt
	s_nop 0
	global_load_dword v110, v[110:111], off offset:16 nt
	s_nop 0
	global_load_dword v111, v[112:113], off offset:24 nt
	global_load_dword v38, v[114:115], off offset:32 nt
	global_load_dword v39, v[116:117], off offset:40 nt
	global_load_dword v108, v[118:119], off offset:48 nt
	global_load_dword v109, v[40:41], off offset:56 nt
	s_waitcnt vmcnt(7)
	v_mul_f32_e32 v40, v103, v107
	s_waitcnt vmcnt(6)
	v_mul_f32_e32 v107, v102, v120
	s_waitcnt vmcnt(5)
	v_mul_f32_e32 v110, v105, v110
	ds_write_b32 v45, v40
	s_waitcnt vmcnt(4)
	v_mul_f32_e32 v111, v104, v111
	s_waitcnt vmcnt(2)
	v_pk_mul_f32 v[38:39], v[34:35], v[38:39]
	ds_write2_b32 v106, v107, v110 offset1:66
	ds_write_b32 v106, v111 offset:528
	s_waitcnt vmcnt(0)
	v_pk_mul_f32 v[40:41], v[36:37], v[108:109]
	s_cbranch_execnz .LBB0_181

; __device__ __forceinline__ void wconv_item(const float* W, int K, int Norig, int Nphys, bf16_t* WT, const float* gA, const float* gB, int split, int mapid, LAS float* scr, int item, int lane) {
;     ...
;     for (int i = 0; i < 32; ++i) { const int kk = 2 * i + (lane >> 5), k = k0 + kk;
;         float v = wv[i];
;         if (gA) v *= (k < split ? gA[k] : gB[k - split]);
;         scr[kk * 33 + (lane & 31)] = v; }
.LBB0_181:
	s_waitcnt vmcnt(0)
	v_add_u32_e32 v34, v44, v56
	ds_write2_b32 v34, v38, v39 offset1:66
	ds_write2_b32 v34, v40, v41 offset0:132 offset1:198
	s_and_b64 vcc, exec, s[4:5]
	v_add_u32_e32 v38, v44, v61
	s_cbranch_vccnz .LBB0_190
	v_or_b32_e32 v36, s80, v60
	v_cmp_gt_i32_e32 vcc, s91, v36
	v_or_b32_e32 v39, s80, v62
	s_ashr_i32 s81, s80, 31
	v_cndmask_b32_e64 v37, -1, 0, vcc
	v_cndmask_b32_e64 v36, v92, 0, vcc
	v_cmp_gt_i32_e32 vcc, s91, v39
	v_or_b32_e32 v39, s80, v63
	v_lshl_add_u64 v[34:35], s[80:81], 0, v[2:3]
	v_cndmask_b32_e64 v41, -1, 0, vcc
	v_cndmask_b32_e64 v40, v92, 0, vcc
	v_cmp_gt_i32_e32 vcc, s91, v39
	v_or_b32_e32 v39, s80, v64
	v_lshl_add_u64 v[34:35], v[34:35], 2, s[24:25]
	v_cndmask_b32_e64 v103, -1, 0, vcc
	v_cndmask_b32_e64 v102, v92, 0, vcc
	v_cmp_gt_i32_e32 vcc, s91, v39
	v_or_b32_e32 v39, s80, v65
	v_lshl_add_u64 v[36:37], v[34:35], 0, v[36:37]
	v_cndmask_b32_e64 v105, -1, 0, vcc
	v_cndmask_b32_e64 v104, v92, 0, vcc
	v_cmp_gt_i32_e32 vcc, s91, v39
	v_or_b32_e32 v39, s80, v67
	v_lshl_add_u64 v[40:41], v[34:35], 0, v[40:41]
	v_cndmask_b32_e64 v107, -1, 0, vcc
	v_cndmask_b32_e64 v106, v92, 0, vcc
	v_cmp_gt_i32_e32 vcc, s91, v39
	v_or_b32_e32 v39, s80, v68
	v_lshl_add_u64 v[102:103], v[34:35], 0, v[102:103]
	v_cndmask_b32_e64 v109, -1, 0, vcc
	v_cndmask_b32_e64 v108, v92, 0, vcc
	v_cmp_gt_i32_e32 vcc, s91, v39
	v_or_b32_e32 v39, s80, v69
	v_lshl_add_u64 v[104:105], v[34:35], 0, v[104:105]
	v_cndmask_b32_e64 v111, -1, 0, vcc
	v_cndmask_b32_e64 v110, v92, 0, vcc
	v_cmp_gt_i32_e32 vcc, s91, v39
	v_lshl_add_u64 v[106:107], v[34:35], 0, v[106:107]
	v_lshl_add_u64 v[108:109], v[34:35], 0, v[108:109]
	v_cndmask_b32_e64 v113, -1, 0, vcc
	v_cndmask_b32_e64 v112, v92, 0, vcc
	v_lshl_add_u64 v[110:111], v[34:35], 0, v[110:111]
	v_lshl_add_u64 v[34:35], v[34:35], 0, v[112:113]
	global_load_dword v39, v[36:37], off offset:64 nt
	global_load_dword v112, v[40:41], off offset:72 nt
	s_nop 0
	global_load_dword v102, v[102:103], off offset:80 nt
	s_nop 0
	global_load_dword v103, v[104:105], off offset:88 nt
	global_load_dword v36, v[106:107], off offset:96 nt
	global_load_dword v37, v[108:109], off offset:104 nt
	global_load_dword v40, v[110:111], off offset:112 nt
	global_load_dword v41, v[34:35], off offset:120 nt
	s_waitcnt vmcnt(7)
	v_mul_f32_e32 v39, v99, v39
	s_waitcnt vmcnt(6)
	v_mul_f32_e32 v104, v98, v112
	s_waitcnt vmcnt(5)
	v_mul_f32_e32 v102, v101, v102
	s_waitcnt vmcnt(4)
	v_mul_f32_e32 v103, v100, v103
	ds_write2_b32 v38, v39, v104 offset1:66
	ds_write2_b32 v38, v102, v103 offset0:132 offset1:198
	s_waitcnt vmcnt(2)
	v_pk_mul_f32 v[34:35], v[30:31], v[36:37]
	s_waitcnt vmcnt(0)
	v_pk_mul_f32 v[36:37], v[32:33], v[40:41]
	s_cbranch_execnz .LBB0_184

; __device__ __forceinline__ void wconv_item(const float* W, int K, int Norig, int Nphys, bf16_t* WT, const float* gA, const float* gB, int split, int mapid, LAS float* scr, int item, int lane) {
;     ...
;     for (int i = 0; i < 32; ++i) { const int kk = 2 * i + (lane >> 5), k = k0 + kk;
;         float v = wv[i];
;         if (gA) v *= (k < split ? gA[k] : gB[k - split]);
;         scr[kk * 33 + (lane & 31)] = v; }
.LBB0_184:
	v_add_u32_e32 v30, v44, v66
	ds_write2_b32 v30, v34, v35 offset1:66
	ds_write2_b32 v30, v36, v37 offset0:132 offset1:198
	s_and_b64 vcc, exec, s[4:5]
	v_add_u32_e32 v34, v44, v71
	s_cbranch_vccnz .LBB0_191
	v_or_b32_e32 v32, s80, v70
	v_cmp_gt_i32_e32 vcc, s91, v32
	v_or_b32_e32 v35, s80, v72
	s_ashr_i32 s81, s80, 31
	v_cndmask_b32_e64 v33, -1, 0, vcc
	v_cndmask_b32_e64 v32, v92, 0, vcc
	v_cmp_gt_i32_e32 vcc, s91, v35
	v_or_b32_e32 v35, s80, v73
	v_lshl_add_u64 v[30:31], s[80:81], 0, v[2:3]
	v_cndmask_b32_e64 v37, -1, 0, vcc
	v_cndmask_b32_e64 v36, v92, 0, vcc
	v_cmp_gt_i32_e32 vcc, s91, v35
	v_or_b32_e32 v35, s80, v74
	v_lshl_add_u64 v[30:31], v[30:31], 2, s[24:25]
	v_cndmask_b32_e64 v39, -1, 0, vcc
	v_cndmask_b32_e64 v38, v92, 0, vcc
	v_cmp_gt_i32_e32 vcc, s91, v35
	v_or_b32_e32 v35, s80, v75
	v_lshl_add_u64 v[32:33], v[30:31], 0, v[32:33]
	v_cndmask_b32_e64 v41, -1, 0, vcc
	v_cndmask_b32_e64 v40, v92, 0, vcc
	v_cmp_gt_i32_e32 vcc, s91, v35
	v_or_b32_e32 v35, s80, v77
	v_lshl_add_u64 v[36:37], v[30:31], 0, v[36:37]
	v_cndmask_b32_e64 v99, -1, 0, vcc
	v_cndmask_b32_e64 v98, v92, 0, vcc
	v_cmp_gt_i32_e32 vcc, s91, v35
	v_or_b32_e32 v35, s80, v78
	v_lshl_add_u64 v[38:39], v[30:31], 0, v[38:39]
	v_cndmask_b32_e64 v101, -1, 0, vcc
	v_cndmask_b32_e64 v100, v92, 0, vcc
	v_cmp_gt_i32_e32 vcc, s91, v35
	v_or_b32_e32 v35, s80, v79
	v_lshl_add_u64 v[40:41], v[30:31], 0, v[40:41]
	v_cndmask_b32_e64 v103, -1, 0, vcc
	v_cndmask_b32_e64 v102, v92, 0, vcc
	v_cmp_gt_i32_e32 vcc, s91, v35
	v_lshl_add_u64 v[98:99], v[30:31], 0, v[98:99]
	v_lshl_add_u64 v[100:101], v[30:31], 0, v[100:101]
	v_cndmask_b32_e64 v105, -1, 0, vcc
	v_cndmask_b32_e64 v104, v92, 0, vcc
	v_lshl_add_u64 v[102:103], v[30:31], 0, v[102:103]
	v_lshl_add_u64 v[30:31], v[30:31], 0, v[104:105]
	global_load_dword v35, v[32:33], off offset:128 nt
	global_load_dword v104, v[36:37], off offset:136 nt
	s_nop 0
	global_load_dword v38, v[38:39], off offset:144 nt
	s_nop 0
	global_load_dword v39, v[40:41], off offset:152 nt
	global_load_dword v32, v[98:99], off offset:160 nt
	global_load_dword v33, v[100:101], off offset:168 nt
	global_load_dword v36, v[102:103], off offset:176 nt
	global_load_dword v37, v[30:31], off offset:184 nt
	s_waitcnt vmcnt(7)
	v_mul_f32_e32 v35, v95, v35
	s_waitcnt vmcnt(6)
	v_mul_f32_e32 v40, v94, v104
	s_waitcnt vmcnt(5)
	v_mul_f32_e32 v38, v97, v38
	s_waitcnt vmcnt(4)
	v_mul_f32_e32 v39, v96, v39
	ds_write2_b32 v34, v35, v40 offset1:66
	ds_write2_b32 v34, v38, v39 offset0:132 offset1:198
	s_waitcnt vmcnt(2)
	v_pk_mul_f32 v[30:31], v[26:27], v[32:33]
	s_waitcnt vmcnt(0)
	v_pk_mul_f32 v[32:33], v[28:29], v[36:37]
	s_cbranch_execnz .LBB0_187

; __device__ __forceinline__ void wconv_item(const float* W, int K, int Norig, int Nphys, bf16_t* WT, const float* gA, const float* gB, int split, int mapid, LAS float* scr, int item, int lane) {
;     ...
;     for (int i = 0; i < 32; ++i) { const int k = k0 + 2 * i + (lane >> 5); wv[i] = (norig >= 0) ? W[(size_t)k * Norig + norig] : 0.f; }
; #pragma unroll
;     for (int i = 0; i < 32; ++i) { const int kk = 2 * i + (lane >> 5), k = k0 + kk;
;         float v = wv[i];
;         if (gA) v *= (k < split ? gA[k] : gB[k - split]);
;         scr[kk * 33 + (lane & 31)] = v; }
.LBB0_187:
	v_add_u32_e32 v26, v44, v76
	ds_write2_b32 v26, v30, v31 offset1:66
	ds_write2_b32 v26, v32, v33 offset0:132 offset1:198
	s_and_b64 vcc, exec, s[4:5]
	v_add_u32_e32 v30, v44, v80
	s_cbranch_vccnz .LBB0_192
	v_or_b32_e32 v28, s80, v83
	v_cmp_gt_i32_e32 vcc, s91, v28
	v_or_b32_e32 v31, s80, v84
	s_ashr_i32 s81, s80, 31
	v_cndmask_b32_e64 v29, -1, 0, vcc
	v_cndmask_b32_e64 v28, v92, 0, vcc
	v_cmp_gt_i32_e32 vcc, s91, v31
	v_or_b32_e32 v31, s80, v85
	v_lshl_add_u64 v[26:27], s[80:81], 0, v[2:3]
	v_cndmask_b32_e64 v33, -1, 0, vcc
	v_cndmask_b32_e64 v32, v92, 0, vcc
	v_cmp_gt_i32_e32 vcc, s91, v31
	v_or_b32_e32 v31, s80, v86
	v_lshl_add_u64 v[26:27], v[26:27], 2, s[24:25]
	v_cndmask_b32_e64 v35, -1, 0, vcc
	v_cndmask_b32_e64 v34, v92, 0, vcc
	v_cmp_gt_i32_e32 vcc, s91, v31
	v_or_b32_e32 v31, s80, v87
	v_lshl_add_u64 v[28:29], v[26:27], 0, v[28:29]
	v_cndmask_b32_e64 v37, -1, 0, vcc
	v_cndmask_b32_e64 v36, v92, 0, vcc
	v_cmp_gt_i32_e32 vcc, s91, v31
	v_or_b32_e32 v31, s80, v88
	v_lshl_add_u64 v[32:33], v[26:27], 0, v[32:33]
	v_cndmask_b32_e64 v39, -1, 0, vcc
	v_cndmask_b32_e64 v38, v92, 0, vcc
	v_cmp_gt_i32_e32 vcc, s91, v31
	v_or_b32_e32 v31, s80, v89
	v_lshl_add_u64 v[34:35], v[26:27], 0, v[34:35]
	v_cndmask_b32_e64 v41, -1, 0, vcc
	v_cndmask_b32_e64 v40, v92, 0, vcc
	v_cmp_gt_i32_e32 vcc, s91, v31
	v_or_b32_e32 v31, s80, v90
	v_lshl_add_u64 v[36:37], v[26:27], 0, v[36:37]
	v_cndmask_b32_e64 v95, -1, 0, vcc
	v_cndmask_b32_e64 v94, v92, 0, vcc
	v_cmp_gt_i32_e32 vcc, s91, v31
	v_lshl_add_u64 v[38:39], v[26:27], 0, v[38:39]
	v_lshl_add_u64 v[40:41], v[26:27], 0, v[40:41]
	v_cndmask_b32_e64 v97, -1, 0, vcc
	v_cndmask_b32_e64 v96, v92, 0, vcc
	v_lshl_add_u64 v[94:95], v[26:27], 0, v[94:95]
	v_lshl_add_u64 v[26:27], v[26:27], 0, v[96:97]
	global_load_dword v31, v[28:29], off offset:192 nt
	global_load_dword v96, v[32:33], off offset:200 nt
	s_nop 0
	global_load_dword v34, v[34:35], off offset:208 nt
	s_nop 0
	global_load_dword v35, v[36:37], off offset:216 nt
	global_load_dword v28, v[38:39], off offset:224 nt
	global_load_dword v29, v[40:41], off offset:232 nt
	global_load_dword v32, v[94:95], off offset:240 nt
	global_load_dword v33, v[26:27], off offset:248 nt
	s_waitcnt vmcnt(7)
	v_mul_f32_e32 v31, v42, v31
	s_waitcnt vmcnt(6)
	v_mul_f32_e32 v36, v4, v96
	s_waitcnt vmcnt(5)
	v_mul_f32_e32 v34, v93, v34
	s_waitcnt vmcnt(4)
	v_mul_f32_e32 v35, v43, v35
	ds_write2_b32 v30, v31, v36 offset1:66
	ds_write2_b32 v30, v34, v35 offset0:132 offset1:198
	s_waitcnt vmcnt(2)
	v_pk_mul_f32 v[26:27], v[22:23], v[28:29]
	s_waitcnt vmcnt(0)
	v_pk_mul_f32 v[28:29], v[24:25], v[32:33]
	s_cbranch_execnz .LBB0_10
	s_branch .LBB0_193

; __device__ __forceinline__ unsigned cvt_pk_bf16(float lo, float hi) { unsigned r; asm volatile("v_cvt_pk_bf16_f32 %0, %1, %2" : "=v"(r) : "v"(lo), "v"(hi)); return r; }
; __device__ __forceinline__ float dot4(f32x4 a) { return (a[0] * a[0] + a[1] * a[1]) + (a[2] * a[2] + a[3] * a[3]); }
; __global__ void __launch_bounds__(512, 2) trunk_fwd(Args args) {
;     ...
;         if (PH(1)) {
;             f32x4 vn[4];
;             if (gw < M) { const f32x4* xr = (const f32x4*)(x_in + (size_t)gw * 1024) + lane;
; #pragma unroll
;                 for (int j = 0; j < 4; ++j) vn[j] = xr[64 * j]; }
;             for (int m = gw; m < M; m += NGW) {
;                 f32x4 v[4]; float s = 0.f;
; #pragma unroll
;                 for (int j = 0; j < 4; ++j) v[j] = vn[j];
;                 if (m + NGW < M) { const f32x4* xr = (const f32x4*)(x_in + (size_t)(m + NGW) * 1024) + lane;
; #pragma unroll
;                     for (int j = 0; j < 4; ++j) vn[j] = xr[64 * j]; }
; #pragma unroll
;                 for (int j = 0; j < 4; ++j) s += dot4(v[j]);
;                 s = wave_sum(s);
;                 u32x2* o8 = (u32x2*)(XB + (size_t)m * 1024) + lane;
; #pragma unroll
;                 for (int j = 0; j < 4; ++j) { u32x2 w; w.x = cvt_pk_bf16(v[j][0], v[j][1]); w.y = cvt_pk_bf16(v[j][2], v[j][3]); o8[64 * j] = w; }
;                 if (lane < 16) XSA[(size_t)m * 16 + lane] = (lane == 0) ? s : 0.f;
.LBB0_217:
	v_mov_b32_e32 v1, v163
	s_lshl_b32 s23, s4, 3
	v_readfirstlane_b32 s5, v1
	s_ashr_i32 s22, s5, 6
	s_add_i32 s12, s22, s23
	s_cmpk_gt_i32 s12, 0x7fff
	v_mbcnt_lo_u32_b32 v42, -1, 0
	s_cbranch_scc1 .LBB0_224
	s_load_dwordx2 s[20:21], s[10:11], 0x0
	s_ashr_i32 s13, s12, 31
	s_lshl_b32 s14, s26, 3
	s_lshl_b64 s[4:5], s[12:13], 12
	v_and_b32_e32 v22, 63, v1
	s_waitcnt lgkmcnt(0)
	s_add_u32 s4, s20, s4
	s_addc_u32 s5, s21, s5
	v_lshlrev_b32_e32 v18, 4, v22
	global_load_dwordx4 v[14:17], v18, s[4:5] nt
	global_load_dwordx4 v[10:13], v18, s[4:5] offset:1024 nt
	global_load_dwordx4 v[6:9], v18, s[4:5] offset:2048 nt
	global_load_dwordx4 v[2:5], v18, s[4:5] offset:3072 nt
	s_ashr_i32 s13, s22, 31
	s_ashr_i32 s15, s23, 31
	s_add_u32 s16, s22, s23
	s_addc_u32 s17, s13, s15
	s_lshl_b64 s[30:31], s[16:17], 6
	s_add_u32 s30, s8, s30
	v_mov_b32_e32 v19, 0
	v_mbcnt_hi_u32_b32 v24, -1, v42
	s_addc_u32 s31, s9, s31
	s_ashr_i32 s15, s14, 31
	v_and_b32_e32 v25, 64, v24
	v_lshlrev_b32_e32 v20, 2, v22
	v_mov_b32_e32 v21, v19
	s_lshl_b64 s[34:35], s[16:17], 11
	s_lshl_b64 s[16:17], s[14:15], 6
	v_xor_b32_e32 v26, 1, v24
	v_add_u32_e32 v25, 64, v25
	v_lshl_add_u64 v[20:21], s[30:31], 0, v[20:21]
	s_add_u32 s30, s8, s34
	v_xor_b32_e32 v27, 2, v24
	v_cmp_lt_i32_e32 vcc, v26, v25
	s_addc_u32 s31, s9, s35
	s_add_i32 s13, s22, s14
	v_xor_b32_e32 v28, 4, v24
	v_cndmask_b32_e32 v26, v24, v26, vcc
	v_cmp_lt_i32_e32 vcc, v27, v25
	s_add_i32 s22, s13, s23
	s_mov_b64 s[18:19], 0x1eb00000
	v_xor_b32_e32 v29, 8, v24
	v_cndmask_b32_e32 v27, v24, v27, vcc
	v_cmp_lt_i32_e32 vcc, v28, v25
	s_ashr_i32 s23, s22, 31
	v_xor_b32_e32 v30, 16, v24
	v_cndmask_b32_e32 v28, v24, v28, vcc
	v_cmp_lt_i32_e32 vcc, v29, v25
	v_lshl_add_u64 v[34:35], v[20:21], 0, s[18:19]
	s_lshl_b64 s[18:19], s[14:15], 11
	s_lshl_b64 s[22:23], s[22:23], 12
	v_xor_b32_e32 v31, 32, v24
	v_cndmask_b32_e32 v29, v24, v29, vcc
	v_cmp_lt_i32_e32 vcc, v30, v25
	s_add_u32 s22, s20, s22
	v_cmp_gt_u32_e64 s[4:5], 16, v22
	v_cmp_eq_u32_e64 s[6:7], 0, v22
	v_lshlrev_b32_e32 v22, 3, v22
	v_mov_b32_e32 v23, v19
	v_cndmask_b32_e32 v30, v24, v30, vcc
	v_cmp_lt_i32_e32 vcc, v31, v25
	s_addc_u32 s23, s21, s23
	s_mov_b64 s[24:25], 0x5500400
	s_mov_b64 s[28:29], 0xc00
	v_cndmask_b32_e32 v24, v24, v31, vcc
	v_lshl_add_u64 v[20:21], s[30:31], 0, v[22:23]
	v_lshl_add_u64 v[18:19], s[22:23], 0, v[18:19]
	v_lshlrev_b32_e32 v40, 2, v26
	v_lshlrev_b32_e32 v41, 2, v27
	v_lshlrev_b32_e32 v43, 2, v28
	v_lshlrev_b32_e32 v44, 2, v29
	v_lshlrev_b32_e32 v45, 2, v30
	v_lshlrev_b32_e32 v46, 2, v24
	v_lshl_add_u64 v[36:37], v[20:21], 0, s[24:25]
	v_lshl_add_u64 v[38:39], v[18:19], 0, s[28:29]
	s_lshl_b64 s[20:21], s[14:15], 12
	s_waitcnt vmcnt(3)
	v_mov_b64_e32 v[20:21], v[16:17]
	s_waitcnt vmcnt(2)
	v_mov_b64_e32 v[24:25], v[12:13]
	s_waitcnt vmcnt(1)
	v_mov_b64_e32 v[28:29], v[8:9]
	s_waitcnt vmcnt(0)
	v_mov_b64_e32 v[32:33], v[4:5]
	v_mov_b64_e32 v[18:19], v[14:15]
	v_mov_b64_e32 v[22:23], v[10:11]
	v_mov_b64_e32 v[26:27], v[6:7]
	v_mov_b64_e32 v[30:31], v[2:3]
	s_branch .LBB0_220

; __global__ void __launch_bounds__(512, 2) trunk_fwd(Args args) {
;     ...
;             for (int m = gw; m < M; m += NGW) {
;                 f32x4 v[4]; float s = 0.f;
; #pragma unroll
;                 for (int j = 0; j < 4; ++j) v[j] = vn[j];
;                 if (m + NGW < M) { const f32x4* xr = (const f32x4*)(x_in + (size_t)(m + NGW) * 1024) + lane;
; #pragma unroll
;                     for (int j = 0; j < 4; ++j) vn[j] = xr[64 * j]; }
.LBB0_220:
	s_add_i32 s12, s12, s14
	s_cmpk_gt_i32 s12, 0x7fff
	s_cselect_b64 s[22:23], -1, 0
	s_and_b64 vcc, exec, s[22:23]
	s_cbranch_vccnz .LBB0_222
	global_load_dwordx4 v[18:21], v[38:39], off offset:-3072 nt
	global_load_dwordx4 v[22:25], v[38:39], off offset:-2048 nt
	global_load_dwordx4 v[26:29], v[38:39], off offset:-1024 nt
	global_load_dwordx4 v[30:33], v[38:39], off nt

; __global__ void __launch_bounds__(512, 2) trunk_fwd(Args args) {
;     ...
;         if (PH(2)) for (int e = (bx * 512 + tid); e < M * 16; e += G * 512) {
;             const int row = e >> 4, f = e & 15;
;             const int fa = f & 3, fb = f >> 2;
;             double inv = (fa == 0) ? 1.0 : (fa == 1) ? 0.5623413251903491 : (fa == 2) ? 0.31622776601683794 : 0.1778279410038923;
;             inv *= (fb == 0) ? 1.0 : (fb == 1) ? 0.1 : (fb == 2) ? 0.01 : 0.001;
;             const double ang = (double)pos[row] * inv;
;             const double kk = __builtin_rint(ang * 0.15915494309189535);
;             double r = __builtin_fma(-kk, 6.283185307179586, ang); r = __builtin_fma(-kk, 2.4492935982947064e-16, r);
;             const double qd = __builtin_rint(r * 0.6366197723675814); const int qi = (int)qd;
;             double y = __builtin_fma(-qd, 1.5707963267948966, r); y = __builtin_fma(-qd, 6.123233995736766e-17, y);
;             const double y2 = y * y;
;             double sp = -7.647163731819816e-13; sp = sp * y2 + 1.6059043836821613e-10; sp = sp * y2 - 2.505210838544172e-08; sp = sp * y2 + 2.7557319223985893e-06;
;             sp = sp * y2 - 1.984126984126984e-04; sp = sp * y2 + 8.333333333333333e-03; sp = sp * y2 - 1.6666666666666666e-01; sp = y + y * y2 * sp;
;             double cp = 4.779477332387385e-14; cp = cp * y2 - 1.1470745597729725e-11; cp = cp * y2 + 2.08767569878681e-09; cp = cp * y2 - 2.755731922398589e-07;
;             cp = cp * y2 + 2.48015873015873e-05; cp = cp * y2 - 1.388888888888889e-03; cp = cp * y2 + 4.1666666666666664e-02; cp = cp * y2 - 0.5; cp = 1.0 + y2 * cp;
;             const int qm = qi & 3;
;             const double sv = (qm == 0) ? sp : (qm == 1) ? cp : (qm == 2) ? -sp : -cp;
;             const double cv = (qm == 0) ? cp : (qm == 1) ? -sp : (qm == 2) ? -cp : sp;
;             COS[e] = (float)cv; SIN[e] = (float)sv;
.LBB0_238:
	s_or_b64 exec, exec, s[4:5]
	v_ashrrev_i32_e32 v40, 4, v2
	v_ashrrev_i32_e32 v41, 31, v40
	s_waitcnt lgkmcnt(0)
	v_lshl_add_u64 v[40:41], v[40:41], 2, s[14:15]
	global_load_dword v48, v[40:41], off nt
	v_mul_f64 v[36:37], v[36:37], v[38:39]
	v_mov_b64_e32 v[38:39], v[14:15]
	v_mov_b64_e32 v[40:41], v[34:35]
	v_mov_b64_e32 v[46:47], v[20:21]
	s_waitcnt vmcnt(0)
	v_cvt_f64_i32_e32 v[48:49], v48
	v_mul_f64 v[36:37], v[36:37], v[48:49]
	v_mul_f64 v[48:49], v[36:37], s[22:23]
	v_rndne_f64_e32 v[48:49], v[48:49]
	v_fmac_f64_e32 v[36:37], s[24:25], v[48:49]
	v_fmac_f64_e32 v[36:37], s[26:27], v[48:49]
	v_mul_f64 v[48:49], v[36:37], s[28:29]
	v_rndne_f64_e32 v[48:49], v[48:49]
	v_fmac_f64_e32 v[36:37], s[30:31], v[48:49]
	v_fmac_f64_e32 v[36:37], s[34:35], v[48:49]
	v_cvt_i32_f64_e32 v50, v[48:49]
	v_mul_f64 v[48:49], v[36:37], v[36:37]
	v_and_b32_e32 v56, 3, v50
	v_fma_f64 v[50:51], s[36:37], v[48:49], v[8:9]
	v_fma_f64 v[54:55], s[38:39], v[48:49], v[24:25]
	v_fma_f64 v[50:51], v[48:49], v[50:51], v[10:11]
	v_fma_f64 v[54:55], v[48:49], v[54:55], v[26:27]
	v_fma_f64 v[50:51], v[48:49], v[50:51], v[12:13]
	v_fma_f64 v[54:55], v[48:49], v[54:55], v[28:29]
	v_fma_f64 v[50:51], v[48:49], v[50:51], v[16:17]
	v_fmac_f64_e32 v[38:39], v[48:49], v[54:55]
	v_fma_f64 v[50:51], v[48:49], v[50:51], v[18:19]
	v_fmac_f64_e32 v[40:41], v[48:49], v[38:39]
	v_mul_f64 v[52:53], v[36:37], v[48:49]
	v_fma_f64 v[38:39], v[48:49], v[50:51], v[22:23]
	v_fmac_f64_e32 v[46:47], v[48:49], v[40:41]
	v_fmac_f64_e32 v[36:37], v[52:53], v[38:39]
	v_fma_f64 v[38:39], v[48:49], v[46:47], -0.5
	v_fma_f64 v[38:39], v[48:49], v[38:39], 1.0
	v_cmp_eq_u32_e32 vcc, 0, v56
	v_cmp_ne_u32_e64 s[10:11], 0, v56
	v_cmp_eq_u32_e64 s[4:5], 1, v56
	v_cmp_ne_u32_e64 s[8:9], 1, v56
	v_cmp_eq_u32_e64 s[6:7], 2, v56
	v_mov_b64_e32 v[40:41], v[38:39]
	s_and_saveexec_b64 s[40:41], s[10:11]
	s_cbranch_execz .LBB0_227
	v_xor_b32_e32 v41, 0x80000000, v37
	v_mov_b32_e32 v40, v36
	s_and_saveexec_b64 s[10:11], s[8:9]
	s_xor_b64 s[8:9], exec, s[10:11]
	s_cbranch_execz .LBB0_226
	v_xor_b32_e32 v40, 0x80000000, v39
	v_cndmask_b32_e64 v41, v37, v40, s[6:7]
	v_cndmask_b32_e64 v40, v36, v38, s[6:7]
	s_branch .LBB0_226

; __device__ __forceinline__ unsigned cvt_pk_bf16(float lo, float hi) { unsigned r; asm volatile("v_cvt_pk_bf16_f32 %0, %1, %2" : "=v"(r) : "v"(lo), "v"(hi)); return r; }
; __device__ __forceinline__ float bf_lo(unsigned w) { return __uint_as_float(w << 16); }
; __device__ __forceinline__ float bf_hi(unsigned w) { return __uint_as_float(w & 0xffff0000u); }
; __global__ void __launch_bounds__(512, 2) trunk_fwd(Args args) {
;     ...
;                 f32x4 pv_n = *(const f32x4*)(pl + (size_t)r0 * PLE + lane * 4);
; #pragma nounroll
;                 for (int rr = 0; rr < 16; ++rr) {
;                     const int r = r0 + rr;
;                     const u32x4 gb = gb_n, gu = gu_n; const f32x4 pv4 = pv_n;
;                     if (rr < 15) { gb_n = *(const u32x4*)(Z + (size_t)(r + 1) * INP + 768 + c0); gu_n = *(const u32x4*)(Z + (size_t)(r + 1) * INP + 1280 + c0);
;                                    pv_n = *(const f32x4*)(pl + (size_t)(r + 1) * PLE + lane * 4); }
;                     float cv[8], uu[8]; float ss = 0.f;
; #pragma unroll
;                     for (int i = 0; i < 4; ++i) {
;                         uu[2 * i] = bf_lo(gu[i]); uu[2 * i + 1] = bf_hi(gu[i]);
;                         cv[2 * i] = bf_lo(gb[i]) * (w0[2 * i] * uu[2 * i] + w1[2 * i] * u1[2 * i] + w2[2 * i] * u2[2 * i]);
;                         cv[2 * i + 1] = bf_hi(gb[i]) * (w0[2 * i + 1] * uu[2 * i + 1] + w1[2 * i + 1] * u1[2 * i + 1] + w2[2 * i + 1] * u2[2 * i + 1]);
;                     }
; #pragma unroll
;                     for (int i = 0; i < 8; ++i) { ss += cv[i] * cv[i]; u2[i] = u1[i]; u1[i] = uu[i]; }
;                     ss = wave_sum(ss);
;                     const float rc = rsqrtf(ss * (1.0f / 512.0f) + EPS);
;                     u32x4 oc;
; #pragma unroll
;                     for (int i = 0; i < 4; ++i) oc[i] = cvt_pk_bf16(cv[2 * i] * rc, cv[2 * i + 1] * rc);
;                     *(u32x4*)(MIX + (size_t)r * 1024 + 512 + c0) = oc;
;                     u32x2 pw; pw.x = cvt_pk_bf16(pv4[0], pv4[1]); pw.y = cvt_pk_bf16(pv4[2], pv4[3]);
;                     *(u32x2*)(PB + (size_t)r * PLE + lane * 4) = pw;
.LBB0_507:
	v_readlane_b32 s4, v254, 2
	s_nop 3
	v_mov_b32_e32 v0, s4
	ds_read_b32 v0, v0
	s_waitcnt lgkmcnt(0)
	v_readfirstlane_b32 s4, v0
	v_readfirstlane_b32 s5, v163
	s_nop 3
	s_cmp_lt_u32 s4, 0x80
	s_cbranch_scc1 .Lpc_skip
	s_load_dwordx2 s[6:7], s[94:95], 0x8
	s_load_dwordx2 s[18:19], s[94:95], 0xc0
	s_lshr_b32 s5, s5, 6
	s_and_b32 s40, s4, 7
	s_lshr_b32 s4, s4, 3
	s_sub_u32 s4, s4, 16
	s_lshl_b32 s4, s4, 3
	s_add_u32 s4, s4, s5
	s_lshl_b32 s4, s4, 5
	s_lshl_b32 s40, s40, 12
	s_add_u32 s40, s40, s4
	s_mov_b32 s41, 0
	v_readlane_b32 s38, v254, 63
	s_mov_b32 s39, 0
	v_and_b32_e32 v2, 63, v163
	v_lshlrev_b32_e32 v3, 3, v2
	v_lshlrev_b32_e32 v2, 4, v2
	s_lshl_b64 s[38:39], s[38:39], 25
	s_lshl_b64 s[4:5], s[40:41], 10
	s_lshl_b64 s[40:41], s[40:41], 9
	s_waitcnt lgkmcnt(0)
	s_add_u32 s6, s6, s38
	s_addc_u32 s7, s7, s39
	s_add_u32 s6, s6, s4
	s_addc_u32 s7, s7, s5
	s_add_u32 s18, s18, 0x1d500000
	s_addc_u32 s19, s19, 0
	s_add_u32 s18, s18, s40
	s_addc_u32 s19, s19, s41
	global_load_dwordx4 v[4:7], v2, s[6:7] nt
	global_load_dwordx4 v[8:11], v2, s[6:7] offset:1024 nt
	global_load_dwordx4 v[12:15], v2, s[6:7] offset:2048 nt
	global_load_dwordx4 v[16:19], v2, s[6:7] offset:3072 nt
	s_add_u32 s6, s6, 0x1000
	s_addc_u32 s7, s7, 0
	global_load_dwordx4 v[20:23], v2, s[6:7] nt
	global_load_dwordx4 v[24:27], v2, s[6:7] offset:1024 nt
	global_load_dwordx4 v[28:31], v2, s[6:7] offset:2048 nt
	global_load_dwordx4 v[32:35], v2, s[6:7] offset:3072 nt
	s_add_u32 s6, s6, 0x1000
	s_addc_u32 s7, s7, 0
	s_waitcnt vmcnt(7)
	v_cvt_pk_bf16_f32 v4, v4, v5
	v_cvt_pk_bf16_f32 v5, v6, v7
	s_waitcnt vmcnt(6)
	v_cvt_pk_bf16_f32 v8, v8, v9
	v_cvt_pk_bf16_f32 v9, v10, v11
	s_waitcnt vmcnt(5)
	v_cvt_pk_bf16_f32 v12, v12, v13
	v_cvt_pk_bf16_f32 v13, v14, v15
	s_waitcnt vmcnt(4)
	v_cvt_pk_bf16_f32 v16, v16, v17
	v_cvt_pk_bf16_f32 v17, v18, v19
	s_waitcnt vmcnt(3)
	v_cvt_pk_bf16_f32 v20, v20, v21
	v_cvt_pk_bf16_f32 v21, v22, v23
	s_waitcnt vmcnt(2)
	v_cvt_pk_bf16_f32 v24, v24, v25
	v_cvt_pk_bf16_f32 v25, v26, v27
	s_waitcnt vmcnt(1)
	v_cvt_pk_bf16_f32 v28, v28, v29
	v_cvt_pk_bf16_f32 v29, v30, v31
	s_waitcnt vmcnt(0)
	v_cvt_pk_bf16_f32 v32, v32, v33
	v_cvt_pk_bf16_f32 v33, v34, v35
	global_store_dwordx2 v3, v[4:5], s[18:19]
	global_store_dwordx2 v3, v[8:9], s[18:19] offset:512
	global_store_dwordx2 v3, v[12:13], s[18:19] offset:1024
	global_store_dwordx2 v3, v[16:17], s[18:19] offset:1536
	global_store_dwordx2 v3, v[20:21], s[18:19] offset:2048
	global_store_dwordx2 v3, v[24:25], s[18:19] offset:2560
	global_store_dwordx2 v3, v[28:29], s[18:19] offset:3072
	global_store_dwordx2 v3, v[32:33], s[18:19] offset:3584
	s_add_u32 s18, s18, 0x1000
	s_addc_u32 s19, s19, 0
	global_load_dwordx4 v[4:7], v2, s[6:7] nt
	global_load_dwordx4 v[8:11], v2, s[6:7] offset:1024 nt
	global_load_dwordx4 v[12:15], v2, s[6:7] offset:2048 nt
	global_load_dwordx4 v[16:19], v2, s[6:7] offset:3072 nt
	s_add_u32 s6, s6, 0x1000
	s_addc_u32 s7, s7, 0
	global_load_dwordx4 v[20:23], v2, s[6:7] nt
	global_load_dwordx4 v[24:27], v2, s[6:7] offset:1024 nt
	global_load_dwordx4 v[28:31], v2, s[6:7] offset:2048 nt
	global_load_dwordx4 v[32:35], v2, s[6:7] offset:3072 nt
	s_add_u32 s6, s6, 0x1000
	s_addc_u32 s7, s7, 0
	s_waitcnt vmcnt(7)
	v_cvt_pk_bf16_f32 v4, v4, v5
	v_cvt_pk_bf16_f32 v5, v6, v7
	s_waitcnt vmcnt(6)
	v_cvt_pk_bf16_f32 v8, v8, v9
	v_cvt_pk_bf16_f32 v9, v10, v11
	s_waitcnt vmcnt(5)
	v_cvt_pk_bf16_f32 v12, v12, v13
	v_cvt_pk_bf16_f32 v13, v14, v15
	s_waitcnt vmcnt(4)
	v_cvt_pk_bf16_f32 v16, v16, v17
	v_cvt_pk_bf16_f32 v17, v18, v19
	s_waitcnt vmcnt(3)
	v_cvt_pk_bf16_f32 v20, v20, v21
	v_cvt_pk_bf16_f32 v21, v22, v23
	s_waitcnt vmcnt(2)
	v_cvt_pk_bf16_f32 v24, v24, v25
	v_cvt_pk_bf16_f32 v25, v26, v27
	s_waitcnt vmcnt(1)
	v_cvt_pk_bf16_f32 v28, v28, v29
	v_cvt_pk_bf16_f32 v29, v30, v31
	s_waitcnt vmcnt(0)
; __device__ __forceinline__ unsigned cvt_pk_bf16(float lo, float hi) { unsigned r; asm volatile("v_cvt_pk_bf16_f32 %0, %1, %2" : "=v"(r) : "v"(lo), "v"(hi)); return r; }
; __device__ __forceinline__ float bf_lo(unsigned w) { return __uint_as_float(w << 16); }
; __device__ __forceinline__ float bf_hi(unsigned w) { return __uint_as_float(w & 0xffff0000u); }
; __global__ void __launch_bounds__(512, 2) trunk_fwd(Args args) {
;     ...
;                 f32x4 pv_n = *(const f32x4*)(pl + (size_t)r0 * PLE + lane * 4);
; #pragma nounroll
;                 for (int rr = 0; rr < 16; ++rr) {
;                     const int r = r0 + rr;
;                     const u32x4 gb = gb_n, gu = gu_n; const f32x4 pv4 = pv_n;
;                     if (rr < 15) { gb_n = *(const u32x4*)(Z + (size_t)(r + 1) * INP + 768 + c0); gu_n = *(const u32x4*)(Z + (size_t)(r + 1) * INP + 1280 + c0);
;                                    pv_n = *(const f32x4*)(pl + (size_t)(r + 1) * PLE + lane * 4); }
;                     float cv[8], uu[8]; float ss = 0.f;
; #pragma unroll
;                     for (int i = 0; i < 4; ++i) {
;                         uu[2 * i] = bf_lo(gu[i]); uu[2 * i + 1] = bf_hi(gu[i]);
;                         cv[2 * i] = bf_lo(gb[i]) * (w0[2 * i] * uu[2 * i] + w1[2 * i] * u1[2 * i] + w2[2 * i] * u2[2 * i]);
;                         cv[2 * i + 1] = bf_hi(gb[i]) * (w0[2 * i + 1] * uu[2 * i + 1] + w1[2 * i + 1] * u1[2 * i + 1] + w2[2 * i + 1] * u2[2 * i + 1]);
;                     }
; #pragma unroll
;                     for (int i = 0; i < 8; ++i) { ss += cv[i] * cv[i]; u2[i] = u1[i]; u1[i] = uu[i]; }
;                     ss = wave_sum(ss);
;                     const float rc = rsqrtf(ss * (1.0f / 512.0f) + EPS);
;                     u32x4 oc;
; #pragma unroll
;                     for (int i = 0; i < 4; ++i) oc[i] = cvt_pk_bf16(cv[2 * i] * rc, cv[2 * i + 1] * rc);
;                     *(u32x4*)(MIX + (size_t)r * 1024 + 512 + c0) = oc;
;                     u32x2 pw; pw.x = cvt_pk_bf16(pv4[0], pv4[1]); pw.y = cvt_pk_bf16(pv4[2], pv4[3]);
;                     *(u32x2*)(PB + (size_t)r * PLE + lane * 4) = pw;
	v_cvt_pk_bf16_f32 v32, v32, v33
	v_cvt_pk_bf16_f32 v33, v34, v35
	global_store_dwordx2 v3, v[4:5], s[18:19]
	global_store_dwordx2 v3, v[8:9], s[18:19] offset:512
	global_store_dwordx2 v3, v[12:13], s[18:19] offset:1024
	global_store_dwordx2 v3, v[16:17], s[18:19] offset:1536
	global_store_dwordx2 v3, v[20:21], s[18:19] offset:2048
	global_store_dwordx2 v3, v[24:25], s[18:19] offset:2560
	global_store_dwordx2 v3, v[28:29], s[18:19] offset:3072
	global_store_dwordx2 v3, v[32:33], s[18:19] offset:3584
	s_add_u32 s18, s18, 0x1000
	s_addc_u32 s19, s19, 0
	global_load_dwordx4 v[4:7], v2, s[6:7] nt
	global_load_dwordx4 v[8:11], v2, s[6:7] offset:1024 nt
	global_load_dwordx4 v[12:15], v2, s[6:7] offset:2048 nt
	global_load_dwordx4 v[16:19], v2, s[6:7] offset:3072 nt
	s_add_u32 s6, s6, 0x1000
	s_addc_u32 s7, s7, 0
	global_load_dwordx4 v[20:23], v2, s[6:7] nt
	global_load_dwordx4 v[24:27], v2, s[6:7] offset:1024 nt
	global_load_dwordx4 v[28:31], v2, s[6:7] offset:2048 nt
	global_load_dwordx4 v[32:35], v2, s[6:7] offset:3072 nt
	s_add_u32 s6, s6, 0x1000
	s_addc_u32 s7, s7, 0
	s_waitcnt vmcnt(7)
	v_cvt_pk_bf16_f32 v4, v4, v5
	v_cvt_pk_bf16_f32 v5, v6, v7
	s_waitcnt vmcnt(6)
	v_cvt_pk_bf16_f32 v8, v8, v9
	v_cvt_pk_bf16_f32 v9, v10, v11
	s_waitcnt vmcnt(5)
	v_cvt_pk_bf16_f32 v12, v12, v13
	v_cvt_pk_bf16_f32 v13, v14, v15
	s_waitcnt vmcnt(4)
	v_cvt_pk_bf16_f32 v16, v16, v17
	v_cvt_pk_bf16_f32 v17, v18, v19
	s_waitcnt vmcnt(3)
	v_cvt_pk_bf16_f32 v20, v20, v21
	v_cvt_pk_bf16_f32 v21, v22, v23
	s_waitcnt vmcnt(2)
	v_cvt_pk_bf16_f32 v24, v24, v25
	v_cvt_pk_bf16_f32 v25, v26, v27
	s_waitcnt vmcnt(1)
	v_cvt_pk_bf16_f32 v28, v28, v29
	v_cvt_pk_bf16_f32 v29, v30, v31
	s_waitcnt vmcnt(0)
	v_cvt_pk_bf16_f32 v32, v32, v33
	v_cvt_pk_bf16_f32 v33, v34, v35
	global_store_dwordx2 v3, v[4:5], s[18:19]
	global_store_dwordx2 v3, v[8:9], s[18:19] offset:512
	global_store_dwordx2 v3, v[12:13], s[18:19] offset:1024
	global_store_dwordx2 v3, v[16:17], s[18:19] offset:1536
	global_store_dwordx2 v3, v[20:21], s[18:19] offset:2048
	global_store_dwordx2 v3, v[24:25], s[18:19] offset:2560
	global_store_dwordx2 v3, v[28:29], s[18:19] offset:3072
	global_store_dwordx2 v3, v[32:33], s[18:19] offset:3584
	s_add_u32 s18, s18, 0x1000
	s_addc_u32 s19, s19, 0
	global_load_dwordx4 v[4:7], v2, s[6:7] nt
	global_load_dwordx4 v[8:11], v2, s[6:7] offset:1024 nt
	global_load_dwordx4 v[12:15], v2, s[6:7] offset:2048 nt
	global_load_dwordx4 v[16:19], v2, s[6:7] offset:3072 nt
	s_add_u32 s6, s6, 0x1000
	s_addc_u32 s7, s7, 0
	global_load_dwordx4 v[20:23], v2, s[6:7] nt
	global_load_dwordx4 v[24:27], v2, s[6:7] offset:1024 nt
	global_load_dwordx4 v[28:31], v2, s[6:7] offset:2048 nt
	global_load_dwordx4 v[32:35], v2, s[6:7] offset:3072 nt
	s_add_u32 s6, s6, 0x1000
	s_addc_u32 s7, s7, 0
	s_waitcnt vmcnt(7)
	v_cvt_pk_bf16_f32 v4, v4, v5
	v_cvt_pk_bf16_f32 v5, v6, v7
	s_waitcnt vmcnt(6)
	v_cvt_pk_bf16_f32 v8, v8, v9
	v_cvt_pk_bf16_f32 v9, v10, v11
	s_waitcnt vmcnt(5)
	v_cvt_pk_bf16_f32 v12, v12, v13
	v_cvt_pk_bf16_f32 v13, v14, v15
	s_waitcnt vmcnt(4)
	v_cvt_pk_bf16_f32 v16, v16, v17
	v_cvt_pk_bf16_f32 v17, v18, v19
	s_waitcnt vmcnt(3)
	v_cvt_pk_bf16_f32 v20, v20, v21
	v_cvt_pk_bf16_f32 v21, v22, v23
	s_waitcnt vmcnt(2)
	v_cvt_pk_bf16_f32 v24, v24, v25
	v_cvt_pk_bf16_f32 v25, v26, v27
	s_waitcnt vmcnt(1)
	v_cvt_pk_bf16_f32 v28, v28, v29
	v_cvt_pk_bf16_f32 v29, v30, v31
	s_waitcnt vmcnt(0)
	v_cvt_pk_bf16_f32 v32, v32, v33
	v_cvt_pk_bf16_f32 v33, v34, v35
	global_store_dwordx2 v3, v[4:5], s[18:19]
	global_store_dwordx2 v3, v[8:9], s[18:19] offset:512
	global_store_dwordx2 v3, v[12:13], s[18:19] offset:1024
	global_store_dwordx2 v3, v[16:17], s[18:19] offset:1536
	global_store_dwordx2 v3, v[20:21], s[18:19] offset:2048
	global_store_dwordx2 v3, v[24:25], s[18:19] offset:2560
	global_store_dwordx2 v3, v[28:29], s[18:19] offset:3072
	global_store_dwordx2 v3, v[32:33], s[18:19] offset:3584
	s_add_u32 s18, s18, 0x1000
	s_addc_u32 s19, s19, 0
